# P0 weight-transpose items: the 32/64 loads of an item are issued together into distinct registers with one wait (was one vmcnt(0) round trip per load pair)
# speedup vs baseline: 1.0136x; 1.0016x over previous
.LBB0_10:
	s_cmpk_gt_i32 s3, 0x7ff
	s_mov_b64 s[0:1], -1
	s_cbranch_scc0 .LBB0_44
	s_cmpk_gt_u32 s3, 0x81f
	s_cbranch_scc0 .LBB0_41
	s_cmpk_gt_u32 s3, 0x83f
	s_cbranch_scc0 .LBB0_38
	s_cmpk_gt_u32 s3, 0x85f
	s_cbranch_scc0 .LBB0_35
	s_cmpk_gt_u32 s3, 0x87f
	s_cbranch_scc0 .LBB0_32
	s_cmpk_gt_u32 s3, 0x89f
	s_cbranch_scc0 .LBB0_29
	s_cmpk_gt_u32 s3, 0x8bf
	s_cbranch_scc0 .LBB0_26
	s_cmpk_gt_u32 s3, 0xabf
	s_cbranch_scc0 .LBB0_23
	s_and_b32 s14, s21, 0x3e0
	s_cmpk_gt_u32 s3, 0xb3f
	v_or_b32_e32 v115, s14, v79
	v_or_b32_e32 v114, s14, v108
	v_or_b32_e32 v113, s14, v109
	v_or_b32_e32 v112, s14, v110
	s_cbranch_scc0 .LBB0_20
	s_and_b32 s0, s19, 0x1ffc0
	s_lshl_b32 s10, s14, 2
	v_or_b32_e32 v116, s0, v3
	v_lshl_add_u64 v[100:101], v[6:7], 0, s[10:11]
	v_lshlrev_b32_e32 v116, 12, v116
	v_mov_b32_e32 v117, v5
	v_lshl_add_u64 v[116:117], v[100:101], 0, v[116:117]
	global_load_dword v125, v[116:117], off
	v_or_b32_e32 v116, s0, v39
	v_lshlrev_b32_e32 v116, 12, v116
	v_mov_b32_e32 v117, v5
	v_lshl_add_u64 v[116:117], v[100:101], 0, v[116:117]
	global_load_dword v128, v[116:117], off
	v_mov_b32_e32 v117, v5
	v_or_b32_e32 v116, s0, v41
	v_lshlrev_b32_e32 v116, 12, v116
	v_lshl_add_u64 v[116:117], v[100:101], 0, v[116:117]
	global_load_dword v130, v[116:117], off
	v_or_b32_e32 v116, s0, v43
	v_lshlrev_b32_e32 v116, 12, v116
	v_mov_b32_e32 v117, v5
	v_lshl_add_u64 v[116:117], v[100:101], 0, v[116:117]
	global_load_dword v131, v[116:117], off
	v_mov_b32_e32 v117, v5
	v_or_b32_e32 v116, s0, v45
	v_lshlrev_b32_e32 v116, 12, v116
	v_lshl_add_u64 v[116:117], v[100:101], 0, v[116:117]
	global_load_dword v132, v[116:117], off
	v_or_b32_e32 v116, s0, v47
	v_lshlrev_b32_e32 v116, 12, v116
	v_mov_b32_e32 v117, v5
	v_lshl_add_u64 v[116:117], v[100:101], 0, v[116:117]
	global_load_dword v133, v[116:117], off
	v_or_b32_e32 v116, s0, v49
	v_lshlrev_b32_e32 v116, 12, v116
	v_mov_b32_e32 v117, v5
	v_lshl_add_u64 v[116:117], v[100:101], 0, v[116:117]
	global_load_dword v134, v[116:117], off
	v_or_b32_e32 v116, s0, v53
	v_lshlrev_b32_e32 v116, 12, v116
	v_mov_b32_e32 v117, v5
	v_lshl_add_u64 v[116:117], v[100:101], 0, v[116:117]
	global_load_dword v135, v[116:117], off
	v_mov_b32_e32 v117, v5
	v_or_b32_e32 v116, s0, v55
	v_lshlrev_b32_e32 v116, 12, v116
	v_lshl_add_u64 v[116:117], v[100:101], 0, v[116:117]
	global_load_dword v136, v[116:117], off
	v_or_b32_e32 v116, s0, v57
	v_lshlrev_b32_e32 v116, 12, v116
	v_mov_b32_e32 v117, v5
	v_lshl_add_u64 v[116:117], v[100:101], 0, v[116:117]
	global_load_dword v137, v[116:117], off
	v_mov_b32_e32 v117, v5
	v_or_b32_e32 v116, s0, v59
	v_lshlrev_b32_e32 v116, 12, v116
	v_lshl_add_u64 v[116:117], v[100:101], 0, v[116:117]
	global_load_dword v138, v[116:117], off
	v_or_b32_e32 v116, s0, v61
	v_lshlrev_b32_e32 v116, 12, v116
	v_mov_b32_e32 v117, v5
	v_lshl_add_u64 v[116:117], v[100:101], 0, v[116:117]
	global_load_dword v139, v[116:117], off
	v_or_b32_e32 v116, s0, v63
	v_lshlrev_b32_e32 v116, 12, v116
	v_mov_b32_e32 v117, v5
	v_lshl_add_u64 v[116:117], v[100:101], 0, v[116:117]
	global_load_dword v140, v[116:117], off
	v_or_b32_e32 v116, s0, v67
	v_lshlrev_b32_e32 v116, 12, v116
	v_mov_b32_e32 v117, v5
	v_lshl_add_u64 v[116:117], v[100:101], 0, v[116:117]
	global_load_dword v141, v[116:117], off
	v_mov_b32_e32 v117, v5
	v_or_b32_e32 v116, s0, v69
	v_lshlrev_b32_e32 v116, 12, v116
	v_lshl_add_u64 v[116:117], v[100:101], 0, v[116:117]
	global_load_dword v142, v[116:117], off
	v_or_b32_e32 v116, s0, v71
	v_lshlrev_b32_e32 v116, 12, v116
	v_mov_b32_e32 v117, v5
	v_lshl_add_u64 v[116:117], v[100:101], 0, v[116:117]
	global_load_dword v143, v[116:117], off
	v_mov_b32_e32 v117, v5
	v_or_b32_e32 v116, s0, v73
	v_lshlrev_b32_e32 v116, 12, v116
	v_lshl_add_u64 v[116:117], v[100:101], 0, v[116:117]
	global_load_dword v144, v[116:117], off
	v_or_b32_e32 v116, s0, v83
	v_lshlrev_b32_e32 v116, 12, v116
	v_mov_b32_e32 v117, v5
	v_lshl_add_u64 v[116:117], v[100:101], 0, v[116:117]
	global_load_dword v145, v[116:117], off
	v_or_b32_e32 v116, s0, v85
	v_lshlrev_b32_e32 v116, 12, v116
	v_mov_b32_e32 v117, v5
	v_lshl_add_u64 v[116:117], v[100:101], 0, v[116:117]
	global_load_dword v146, v[116:117], off
	v_or_b32_e32 v116, s0, v87
	v_lshlrev_b32_e32 v116, 12, v116
	v_mov_b32_e32 v117, v5
	v_lshl_add_u64 v[116:117], v[100:101], 0, v[116:117]
	global_load_dword v148, v[116:117], off
	v_mov_b32_e32 v117, v5
	v_or_b32_e32 v116, s0, v89
	v_lshlrev_b32_e32 v116, 12, v116
	v_lshl_add_u64 v[116:117], v[100:101], 0, v[116:117]
	global_load_dword v150, v[116:117], off
	v_or_b32_e32 v116, s0, v91
	v_lshlrev_b32_e32 v116, 12, v116
	v_mov_b32_e32 v117, v5
	v_lshl_add_u64 v[116:117], v[100:101], 0, v[116:117]
	global_load_dword v151, v[116:117], off
	v_mov_b32_e32 v117, v5
	v_or_b32_e32 v116, s0, v93
	v_lshlrev_b32_e32 v116, 12, v116
	v_lshl_add_u64 v[116:117], v[100:101], 0, v[116:117]
	global_load_dword v152, v[116:117], off
	v_or_b32_e32 v116, s0, v95
	v_lshlrev_b32_e32 v116, 12, v116
	v_mov_b32_e32 v117, v5
	v_lshl_add_u64 v[116:117], v[100:101], 0, v[116:117]
	global_load_dword v153, v[116:117], off
	v_or_b32_e32 v116, s0, v97
	v_lshlrev_b32_e32 v116, 12, v116
	v_mov_b32_e32 v117, v5
	v_lshl_add_u64 v[116:117], v[100:101], 0, v[116:117]
	global_load_dword v154, v[116:117], off
	v_or_b32_e32 v116, s0, v99
	v_lshlrev_b32_e32 v116, 12, v116
	v_mov_b32_e32 v117, v5
	v_lshl_add_u64 v[116:117], v[100:101], 0, v[116:117]
	global_load_dword v155, v[116:117], off
	v_mov_b32_e32 v117, v5
	v_or_b32_e32 v116, s0, v102
	v_lshlrev_b32_e32 v116, 12, v116
	v_lshl_add_u64 v[116:117], v[100:101], 0, v[116:117]
	global_load_dword v156, v[116:117], off
	v_or_b32_e32 v116, s0, v103
	v_lshlrev_b32_e32 v116, 12, v116
	v_mov_b32_e32 v117, v5
	v_lshl_add_u64 v[116:117], v[100:101], 0, v[116:117]
	global_load_dword v157, v[116:117], off
	v_mov_b32_e32 v117, v5
	v_or_b32_e32 v116, s0, v104
	v_lshlrev_b32_e32 v116, 12, v116
	v_lshl_add_u64 v[116:117], v[100:101], 0, v[116:117]
	global_load_dword v158, v[116:117], off
	v_or_b32_e32 v116, s0, v105
	v_lshlrev_b32_e32 v116, 12, v116
	v_mov_b32_e32 v117, v5
	v_lshl_add_u64 v[116:117], v[100:101], 0, v[116:117]
	global_load_dword v159, v[116:117], off
	v_mov_b32_e32 v117, v5
	v_or_b32_e32 v116, s0, v106
	v_lshlrev_b32_e32 v116, 12, v116
	v_lshl_add_u64 v[116:117], v[100:101], 0, v[116:117]
	global_load_dword v160, v[116:117], off
	v_or_b32_e32 v116, s0, v107
	v_lshlrev_b32_e32 v116, 12, v116
	v_mov_b32_e32 v117, v5
	v_lshl_add_u64 v[100:101], v[100:101], 0, v[116:117]
	global_load_dword v161, v[100:101], off
	s_waitcnt vmcnt(0)
	v_add_u32_e32 v119, v19, v37
	s_lshl_b32 s10, s0, 1
	ds_write2_b32 v119, v125, v128 offset1:66
	ds_write2_b32 v119, v130, v131 offset0:132 offset1:198
	v_add_u32_e32 v117, 0x400, v119
	v_add_u32_e32 v119, v19, v51
	ds_write2_b32 v117, v132, v133 offset0:8 offset1:74
	ds_write2_b32 v119, v134, v135 offset1:66
	ds_write2_b32 v119, v136, v137 offset0:132 offset1:198
	v_add_u32_e32 v117, 0x400, v119
	v_add_u32_e32 v119, v19, v65
	ds_write2_b32 v117, v138, v139 offset0:8 offset1:74
	ds_write2_b32 v119, v140, v141 offset1:66
	ds_write2_b32 v119, v142, v143 offset0:132 offset1:198
	v_add_u32_e32 v117, 0x400, v119
	v_add_u32_e32 v119, v19, v75
	ds_write2_b32 v117, v144, v145 offset0:8 offset1:74
	ds_write2_b32 v119, v146, v148 offset1:66
	ds_write2_b32 v119, v150, v151 offset0:132 offset1:198
	v_add_u32_e32 v117, 0x400, v119
	v_add_u32_e32 v119, v19, v77
	ds_write2_b32 v117, v152, v153 offset0:8 offset1:74
	ds_write2_b32 v119, v154, v155 offset1:66
	ds_write2_b32 v119, v156, v157 offset0:132 offset1:198
	v_add_u32_e32 v119, 0x400, v119
	ds_write2_b32 v119, v158, v159 offset0:8 offset1:74
	s_mov_b64 s[0:1], 0
	ds_write2_b32 v119, v160, v161 offset0:140 offset1:206
	s_waitcnt lgkmcnt(0)
	ds_read2_b32 v[116:117], v81 offset1:33
	s_waitcnt lgkmcnt(0)
	v_cvt_pk_bf16_f32 v116, v116, v117
	ds_read2_b32 v[118:119], v81 offset0:66 offset1:99
	s_waitcnt lgkmcnt(0)
	v_cvt_pk_bf16_f32 v117, v118, v119
	ds_read2_b32 v[118:119], v81 offset0:132 offset1:165
	s_waitcnt lgkmcnt(0)
	v_cvt_pk_bf16_f32 v118, v118, v119
	ds_read2_b32 v[120:121], v81 offset0:198 offset1:231
	v_lshl_add_u64 v[100:101], v[8:9], 0, s[10:11]
	s_waitcnt lgkmcnt(0)
	v_cvt_pk_bf16_f32 v119, v120, v121
	v_lshlrev_b32_e32 v120, 11, v115
	v_mov_b32_e32 v121, v5
	v_lshl_add_u64 v[120:121], v[100:101], 0, v[120:121]
	global_store_dwordx4 v[120:121], v[116:119], off
	ds_read2_b32 v[116:117], v81 offset0:8 offset1:41
	s_waitcnt lgkmcnt(0)
	v_cvt_pk_bf16_f32 v116, v116, v117
	ds_read2_b32 v[118:119], v81 offset0:74 offset1:107
	s_waitcnt lgkmcnt(0)
	v_cvt_pk_bf16_f32 v117, v118, v119
	ds_read2_b32 v[118:119], v81 offset0:140 offset1:173
	s_waitcnt lgkmcnt(0)
	v_cvt_pk_bf16_f32 v118, v118, v119
	ds_read2_b32 v[120:121], v81 offset0:206 offset1:239
	s_waitcnt lgkmcnt(0)
	v_cvt_pk_bf16_f32 v119, v120, v121
	v_lshlrev_b32_e32 v120, 11, v114
	v_mov_b32_e32 v121, v5
	v_lshl_add_u64 v[120:121], v[100:101], 0, v[120:121]
	global_store_dwordx4 v[120:121], v[116:119], off
	ds_read2_b32 v[116:117], v81 offset0:16 offset1:49
	s_waitcnt lgkmcnt(0)
	v_cvt_pk_bf16_f32 v116, v116, v117
	ds_read2_b32 v[118:119], v81 offset0:82 offset1:115
	s_waitcnt lgkmcnt(0)
	v_cvt_pk_bf16_f32 v117, v118, v119
	ds_read2_b32 v[118:119], v81 offset0:148 offset1:181
	s_waitcnt lgkmcnt(0)
	v_cvt_pk_bf16_f32 v118, v118, v119
	ds_read2_b32 v[120:121], v81 offset0:214 offset1:247
	s_waitcnt lgkmcnt(0)
	v_cvt_pk_bf16_f32 v119, v120, v121
	v_lshlrev_b32_e32 v120, 11, v113
	v_mov_b32_e32 v121, v5
	v_lshl_add_u64 v[120:121], v[100:101], 0, v[120:121]
	global_store_dwordx4 v[120:121], v[116:119], off
	ds_read2_b32 v[116:117], v81 offset0:24 offset1:57
	s_waitcnt lgkmcnt(0)
	v_cvt_pk_bf16_f32 v116, v116, v117
	ds_read2_b32 v[118:119], v81 offset0:90 offset1:123
	s_waitcnt lgkmcnt(0)
	v_cvt_pk_bf16_f32 v117, v118, v119
	ds_read2_b32 v[118:119], v81 offset0:156 offset1:189
	s_waitcnt lgkmcnt(0)
	v_cvt_pk_bf16_f32 v118, v118, v119
	ds_read2_b32 v[120:121], v81 offset0:222 offset1:255
	s_waitcnt lgkmcnt(0)
	v_cvt_pk_bf16_f32 v119, v120, v121
	v_lshlrev_b32_e32 v120, 11, v112
	v_mov_b32_e32 v121, v5
	v_lshl_add_u64 v[100:101], v[100:101], 0, v[120:121]
	global_store_dwordx4 v[100:101], v[116:119], off
	s_waitcnt lgkmcnt(0)
.LBB0_20:
	s_andn2_b64 vcc, exec, s[0:1]
	s_cbranch_vccnz .LBB0_22
	s_add_i32 s0, s19, 0xfffe1700
	s_and_b32 s0, s0, 0x1c0
	s_lshl_b32 s10, s14, 2
	v_or_b32_e32 v116, s0, v3
	v_lshl_add_u64 v[100:101], v[10:11], 0, s[10:11]
	v_lshlrev_b32_e32 v116, 12, v116
	v_mov_b32_e32 v117, v5
	v_lshl_add_u64 v[116:117], v[100:101], 0, v[116:117]
	global_load_dword v125, v[116:117], off
	v_or_b32_e32 v116, s0, v39
	v_lshlrev_b32_e32 v116, 12, v116
	v_mov_b32_e32 v117, v5
	v_lshl_add_u64 v[116:117], v[100:101], 0, v[116:117]
	global_load_dword v128, v[116:117], off
	v_mov_b32_e32 v117, v5
	v_or_b32_e32 v116, s0, v41
	v_lshlrev_b32_e32 v116, 12, v116
	v_lshl_add_u64 v[116:117], v[100:101], 0, v[116:117]
	global_load_dword v130, v[116:117], off
	v_or_b32_e32 v116, s0, v43
	v_lshlrev_b32_e32 v116, 12, v116
	v_mov_b32_e32 v117, v5
	v_lshl_add_u64 v[116:117], v[100:101], 0, v[116:117]
	global_load_dword v131, v[116:117], off
	v_mov_b32_e32 v117, v5
	v_or_b32_e32 v116, s0, v45
	v_lshlrev_b32_e32 v116, 12, v116
	v_lshl_add_u64 v[116:117], v[100:101], 0, v[116:117]
	global_load_dword v132, v[116:117], off
	v_or_b32_e32 v116, s0, v47
	v_lshlrev_b32_e32 v116, 12, v116
	v_mov_b32_e32 v117, v5
	v_lshl_add_u64 v[116:117], v[100:101], 0, v[116:117]
	global_load_dword v133, v[116:117], off
	v_or_b32_e32 v116, s0, v49
	v_lshlrev_b32_e32 v116, 12, v116
	v_mov_b32_e32 v117, v5
	v_lshl_add_u64 v[116:117], v[100:101], 0, v[116:117]
	global_load_dword v134, v[116:117], off
	v_or_b32_e32 v116, s0, v53
	v_lshlrev_b32_e32 v116, 12, v116
	v_mov_b32_e32 v117, v5
	v_lshl_add_u64 v[116:117], v[100:101], 0, v[116:117]
	global_load_dword v135, v[116:117], off
	v_mov_b32_e32 v117, v5
	v_or_b32_e32 v116, s0, v55
	v_lshlrev_b32_e32 v116, 12, v116
	v_lshl_add_u64 v[116:117], v[100:101], 0, v[116:117]
	global_load_dword v136, v[116:117], off
	v_or_b32_e32 v116, s0, v57
	v_lshlrev_b32_e32 v116, 12, v116
	v_mov_b32_e32 v117, v5
	v_lshl_add_u64 v[116:117], v[100:101], 0, v[116:117]
	global_load_dword v137, v[116:117], off
	v_mov_b32_e32 v117, v5
	v_or_b32_e32 v116, s0, v59
	v_lshlrev_b32_e32 v116, 12, v116
	v_lshl_add_u64 v[116:117], v[100:101], 0, v[116:117]
	global_load_dword v138, v[116:117], off
	v_or_b32_e32 v116, s0, v61
	v_lshlrev_b32_e32 v116, 12, v116
	v_mov_b32_e32 v117, v5
	v_lshl_add_u64 v[116:117], v[100:101], 0, v[116:117]
	global_load_dword v139, v[116:117], off
	v_or_b32_e32 v116, s0, v63
	v_lshlrev_b32_e32 v116, 12, v116
	v_mov_b32_e32 v117, v5
	v_lshl_add_u64 v[116:117], v[100:101], 0, v[116:117]
	global_load_dword v140, v[116:117], off
	v_or_b32_e32 v116, s0, v67
	v_lshlrev_b32_e32 v116, 12, v116
	v_mov_b32_e32 v117, v5
	v_lshl_add_u64 v[116:117], v[100:101], 0, v[116:117]
	global_load_dword v141, v[116:117], off
	v_mov_b32_e32 v117, v5
	v_or_b32_e32 v116, s0, v69
	v_lshlrev_b32_e32 v116, 12, v116
	v_lshl_add_u64 v[116:117], v[100:101], 0, v[116:117]
	global_load_dword v142, v[116:117], off
	v_or_b32_e32 v116, s0, v71
	v_lshlrev_b32_e32 v116, 12, v116
	v_mov_b32_e32 v117, v5
	v_lshl_add_u64 v[116:117], v[100:101], 0, v[116:117]
	global_load_dword v143, v[116:117], off
	v_mov_b32_e32 v117, v5
	v_or_b32_e32 v116, s0, v73
	v_lshlrev_b32_e32 v116, 12, v116
	v_lshl_add_u64 v[116:117], v[100:101], 0, v[116:117]
	global_load_dword v144, v[116:117], off
	v_or_b32_e32 v116, s0, v83
	v_lshlrev_b32_e32 v116, 12, v116
	v_mov_b32_e32 v117, v5
	v_lshl_add_u64 v[116:117], v[100:101], 0, v[116:117]
	global_load_dword v145, v[116:117], off
	v_or_b32_e32 v116, s0, v85
	v_lshlrev_b32_e32 v116, 12, v116
	v_mov_b32_e32 v117, v5
	v_lshl_add_u64 v[116:117], v[100:101], 0, v[116:117]
	global_load_dword v146, v[116:117], off
	v_or_b32_e32 v116, s0, v87
	v_lshlrev_b32_e32 v116, 12, v116
	v_mov_b32_e32 v117, v5
	v_lshl_add_u64 v[116:117], v[100:101], 0, v[116:117]
	global_load_dword v148, v[116:117], off
	v_mov_b32_e32 v117, v5
	v_or_b32_e32 v116, s0, v89
	v_lshlrev_b32_e32 v116, 12, v116
	v_lshl_add_u64 v[116:117], v[100:101], 0, v[116:117]
	global_load_dword v150, v[116:117], off
	v_or_b32_e32 v116, s0, v91
	v_lshlrev_b32_e32 v116, 12, v116
	v_mov_b32_e32 v117, v5
	v_lshl_add_u64 v[116:117], v[100:101], 0, v[116:117]
	global_load_dword v151, v[116:117], off
	v_mov_b32_e32 v117, v5
	v_or_b32_e32 v116, s0, v93
	v_lshlrev_b32_e32 v116, 12, v116
	v_lshl_add_u64 v[116:117], v[100:101], 0, v[116:117]
	global_load_dword v152, v[116:117], off
	v_or_b32_e32 v116, s0, v95
	v_lshlrev_b32_e32 v116, 12, v116
	v_mov_b32_e32 v117, v5
	v_lshl_add_u64 v[116:117], v[100:101], 0, v[116:117]
	global_load_dword v153, v[116:117], off
	v_or_b32_e32 v116, s0, v97
	v_lshlrev_b32_e32 v116, 12, v116
	v_mov_b32_e32 v117, v5
	v_lshl_add_u64 v[116:117], v[100:101], 0, v[116:117]
	global_load_dword v154, v[116:117], off
	v_or_b32_e32 v116, s0, v99
	v_lshlrev_b32_e32 v116, 12, v116
	v_mov_b32_e32 v117, v5
	v_lshl_add_u64 v[116:117], v[100:101], 0, v[116:117]
	global_load_dword v155, v[116:117], off
	v_mov_b32_e32 v117, v5
	v_or_b32_e32 v116, s0, v102
	v_lshlrev_b32_e32 v116, 12, v116
	v_lshl_add_u64 v[116:117], v[100:101], 0, v[116:117]
	global_load_dword v156, v[116:117], off
	v_or_b32_e32 v116, s0, v103
	v_lshlrev_b32_e32 v116, 12, v116
	v_mov_b32_e32 v117, v5
	v_lshl_add_u64 v[116:117], v[100:101], 0, v[116:117]
	global_load_dword v157, v[116:117], off
	v_mov_b32_e32 v117, v5
	v_or_b32_e32 v116, s0, v104
	v_lshlrev_b32_e32 v116, 12, v116
	v_lshl_add_u64 v[116:117], v[100:101], 0, v[116:117]
	global_load_dword v158, v[116:117], off
	v_or_b32_e32 v116, s0, v105
	v_lshlrev_b32_e32 v116, 12, v116
	v_mov_b32_e32 v117, v5
	v_lshl_add_u64 v[116:117], v[100:101], 0, v[116:117]
	global_load_dword v159, v[116:117], off
	v_mov_b32_e32 v117, v5
	v_or_b32_e32 v116, s0, v106
	v_lshlrev_b32_e32 v116, 12, v116
	v_lshl_add_u64 v[116:117], v[100:101], 0, v[116:117]
	global_load_dword v160, v[116:117], off
	v_or_b32_e32 v116, s0, v107
	v_lshlrev_b32_e32 v116, 12, v116
	v_mov_b32_e32 v117, v5
	v_lshl_add_u64 v[100:101], v[100:101], 0, v[116:117]
	global_load_dword v161, v[100:101], off
	s_waitcnt vmcnt(0)
	v_add_u32_e32 v119, v19, v37
	s_lshl_b32 s10, s0, 1
	v_lshlrev_b32_e32 v114, 9, v114
	v_lshlrev_b32_e32 v112, 9, v112
	ds_write2_b32 v119, v125, v128 offset1:66
	ds_write2_b32 v119, v130, v131 offset0:132 offset1:198
	v_add_u32_e32 v117, 0x400, v119
	v_add_u32_e32 v119, v19, v51
	ds_write2_b32 v117, v132, v133 offset0:8 offset1:74
	ds_write2_b32 v119, v134, v135 offset1:66
	ds_write2_b32 v119, v136, v137 offset0:132 offset1:198
	v_add_u32_e32 v117, 0x400, v119
	v_add_u32_e32 v119, v19, v65
	ds_write2_b32 v117, v138, v139 offset0:8 offset1:74
	ds_write2_b32 v119, v140, v141 offset1:66
	ds_write2_b32 v119, v142, v143 offset0:132 offset1:198
	v_add_u32_e32 v117, 0x400, v119
	v_add_u32_e32 v119, v19, v75
	ds_write2_b32 v117, v144, v145 offset0:8 offset1:74
	ds_write2_b32 v119, v146, v148 offset1:66
	ds_write2_b32 v119, v150, v151 offset0:132 offset1:198
	v_add_u32_e32 v117, 0x400, v119
	v_add_u32_e32 v119, v19, v77
	ds_write2_b32 v117, v152, v153 offset0:8 offset1:74
	ds_write2_b32 v119, v154, v155 offset1:66
	ds_write2_b32 v119, v156, v157 offset0:132 offset1:198
	v_add_u32_e32 v119, 0x400, v119
	ds_write2_b32 v119, v158, v159 offset0:8 offset1:74
	ds_write2_b32 v119, v160, v161 offset0:140 offset1:206
	s_waitcnt lgkmcnt(0)
	ds_read2_b32 v[116:117], v81 offset1:33
	s_waitcnt lgkmcnt(0)
	v_cvt_pk_bf16_f32 v116, v116, v117
	ds_read2_b32 v[118:119], v81 offset0:66 offset1:99
	s_waitcnt lgkmcnt(0)
	v_cvt_pk_bf16_f32 v117, v118, v119
	ds_read2_b32 v[118:119], v81 offset0:132 offset1:165
	s_waitcnt lgkmcnt(0)
	v_cvt_pk_bf16_f32 v118, v118, v119
	ds_read2_b32 v[120:121], v81 offset0:198 offset1:231
	v_lshl_add_u64 v[100:101], v[12:13], 0, s[10:11]
	s_waitcnt lgkmcnt(0)
	v_cvt_pk_bf16_f32 v119, v120, v121
	v_lshlrev_b32_e32 v120, 9, v115
	v_mov_b32_e32 v121, v5
	v_lshl_add_u64 v[120:121], v[100:101], 0, v[120:121]
	global_store_dwordx4 v[120:121], v[116:119], off
	ds_read2_b32 v[116:117], v81 offset0:8 offset1:41
	v_mov_b32_e32 v115, v5
	s_waitcnt lgkmcnt(0)
	v_cvt_pk_bf16_f32 v116, v116, v117
	ds_read2_b32 v[118:119], v81 offset0:74 offset1:107
	s_waitcnt lgkmcnt(0)
	v_cvt_pk_bf16_f32 v117, v118, v119
	ds_read2_b32 v[118:119], v81 offset0:140 offset1:173
	v_lshl_add_u64 v[114:115], v[100:101], 0, v[114:115]
	s_waitcnt lgkmcnt(0)
	v_cvt_pk_bf16_f32 v118, v118, v119
	ds_read2_b32 v[120:121], v81 offset0:206 offset1:239
	s_waitcnt lgkmcnt(0)
	v_cvt_pk_bf16_f32 v119, v120, v121
	global_store_dwordx4 v[114:115], v[116:119], off
	ds_read2_b32 v[114:115], v81 offset0:16 offset1:49
	s_waitcnt lgkmcnt(0)
	v_cvt_pk_bf16_f32 v114, v114, v115
	ds_read2_b32 v[116:117], v81 offset0:82 offset1:115
	s_waitcnt lgkmcnt(0)
	v_cvt_pk_bf16_f32 v115, v116, v117
	ds_read2_b32 v[116:117], v81 offset0:148 offset1:181
	s_waitcnt lgkmcnt(0)
	v_cvt_pk_bf16_f32 v116, v116, v117
	ds_read2_b32 v[118:119], v81 offset0:214 offset1:247
	s_waitcnt lgkmcnt(0)
	v_cvt_pk_bf16_f32 v117, v118, v119
	v_lshlrev_b32_e32 v118, 9, v113
	v_mov_b32_e32 v119, v5
	v_lshl_add_u64 v[118:119], v[100:101], 0, v[118:119]
	global_store_dwordx4 v[118:119], v[114:117], off
	ds_read2_b32 v[114:115], v81 offset0:24 offset1:57
	v_mov_b32_e32 v113, v5
	s_waitcnt lgkmcnt(0)
	v_cvt_pk_bf16_f32 v114, v114, v115
	ds_read2_b32 v[116:117], v81 offset0:90 offset1:123
	s_waitcnt lgkmcnt(0)
	v_cvt_pk_bf16_f32 v115, v116, v117
	ds_read2_b32 v[116:117], v81 offset0:156 offset1:189
	v_lshl_add_u64 v[100:101], v[100:101], 0, v[112:113]
	s_waitcnt lgkmcnt(0)
	v_cvt_pk_bf16_f32 v116, v116, v117
	ds_read2_b32 v[118:119], v81 offset0:222 offset1:255
	s_waitcnt lgkmcnt(0)
	v_cvt_pk_bf16_f32 v117, v118, v119
	global_store_dwordx4 v[100:101], v[114:117], off
	s_waitcnt lgkmcnt(0)

.LBB0_23:
	s_andn2_b64 vcc, exec, s[0:1]
	s_cbranch_vccnz .LBB0_25
	s_add_i32 s0, s19, 0x500
	s_and_b32 s1, s0, 0x1ffc0
	s_and_b32 s0, s21, 0x3e0
	s_lshl_b32 s10, s0, 2
	v_or_b32_e32 v112, s1, v3
	v_lshl_add_u64 v[100:101], v[14:15], 0, s[10:11]
	v_lshlrev_b32_e32 v112, 12, v112
	v_mov_b32_e32 v113, v5
	v_lshl_add_u64 v[112:113], v[100:101], 0, v[112:113]
	global_load_dword v125, v[112:113], off
	v_or_b32_e32 v112, s1, v39
	v_lshlrev_b32_e32 v112, 12, v112
	v_mov_b32_e32 v113, v5
	v_lshl_add_u64 v[112:113], v[100:101], 0, v[112:113]
	global_load_dword v128, v[112:113], off
	v_mov_b32_e32 v113, v5
	v_or_b32_e32 v112, s1, v41
	v_lshlrev_b32_e32 v112, 12, v112
	v_lshl_add_u64 v[112:113], v[100:101], 0, v[112:113]
	global_load_dword v130, v[112:113], off
	v_or_b32_e32 v112, s1, v43
	v_lshlrev_b32_e32 v112, 12, v112
	v_mov_b32_e32 v113, v5
	v_lshl_add_u64 v[112:113], v[100:101], 0, v[112:113]
	global_load_dword v131, v[112:113], off
	v_mov_b32_e32 v113, v5
	v_or_b32_e32 v112, s1, v45
	v_lshlrev_b32_e32 v112, 12, v112
	v_lshl_add_u64 v[112:113], v[100:101], 0, v[112:113]
	global_load_dword v132, v[112:113], off
	v_or_b32_e32 v112, s1, v47
	v_lshlrev_b32_e32 v112, 12, v112
	v_mov_b32_e32 v113, v5
	v_lshl_add_u64 v[112:113], v[100:101], 0, v[112:113]
	global_load_dword v133, v[112:113], off
	v_or_b32_e32 v112, s1, v49
	v_lshlrev_b32_e32 v112, 12, v112
	v_mov_b32_e32 v113, v5
	v_lshl_add_u64 v[112:113], v[100:101], 0, v[112:113]
	global_load_dword v134, v[112:113], off
	v_or_b32_e32 v112, s1, v53
	v_lshlrev_b32_e32 v112, 12, v112
	v_mov_b32_e32 v113, v5
	v_lshl_add_u64 v[112:113], v[100:101], 0, v[112:113]
	global_load_dword v135, v[112:113], off
	v_mov_b32_e32 v113, v5
	v_or_b32_e32 v112, s1, v55
	v_lshlrev_b32_e32 v112, 12, v112
	v_lshl_add_u64 v[112:113], v[100:101], 0, v[112:113]
	global_load_dword v136, v[112:113], off
	v_or_b32_e32 v112, s1, v57
	v_lshlrev_b32_e32 v112, 12, v112
	v_mov_b32_e32 v113, v5
	v_lshl_add_u64 v[112:113], v[100:101], 0, v[112:113]
	global_load_dword v137, v[112:113], off
	v_mov_b32_e32 v113, v5
	v_or_b32_e32 v112, s1, v59
	v_lshlrev_b32_e32 v112, 12, v112
	v_lshl_add_u64 v[112:113], v[100:101], 0, v[112:113]
	global_load_dword v138, v[112:113], off
	v_or_b32_e32 v112, s1, v61
	v_lshlrev_b32_e32 v112, 12, v112
	v_mov_b32_e32 v113, v5
	v_lshl_add_u64 v[112:113], v[100:101], 0, v[112:113]
	global_load_dword v139, v[112:113], off
	v_or_b32_e32 v112, s1, v63
	v_lshlrev_b32_e32 v112, 12, v112
	v_mov_b32_e32 v113, v5
	v_lshl_add_u64 v[112:113], v[100:101], 0, v[112:113]
	global_load_dword v140, v[112:113], off
	v_or_b32_e32 v112, s1, v67
	v_lshlrev_b32_e32 v112, 12, v112
	v_mov_b32_e32 v113, v5
	v_lshl_add_u64 v[112:113], v[100:101], 0, v[112:113]
	global_load_dword v141, v[112:113], off
	v_mov_b32_e32 v113, v5
	v_or_b32_e32 v112, s1, v69
	v_lshlrev_b32_e32 v112, 12, v112
	v_lshl_add_u64 v[112:113], v[100:101], 0, v[112:113]
	global_load_dword v142, v[112:113], off
	v_or_b32_e32 v112, s1, v71
	v_lshlrev_b32_e32 v112, 12, v112
	v_mov_b32_e32 v113, v5
	v_lshl_add_u64 v[112:113], v[100:101], 0, v[112:113]
	global_load_dword v143, v[112:113], off
	v_mov_b32_e32 v113, v5
	v_or_b32_e32 v112, s1, v73
	v_lshlrev_b32_e32 v112, 12, v112
	v_lshl_add_u64 v[112:113], v[100:101], 0, v[112:113]
	global_load_dword v144, v[112:113], off
	v_or_b32_e32 v112, s1, v83
	v_lshlrev_b32_e32 v112, 12, v112
	v_mov_b32_e32 v113, v5
	v_lshl_add_u64 v[112:113], v[100:101], 0, v[112:113]
	global_load_dword v145, v[112:113], off
	v_or_b32_e32 v112, s1, v85
	v_lshlrev_b32_e32 v112, 12, v112
	v_mov_b32_e32 v113, v5
	v_lshl_add_u64 v[112:113], v[100:101], 0, v[112:113]
	global_load_dword v146, v[112:113], off
	v_or_b32_e32 v112, s1, v87
	v_lshlrev_b32_e32 v112, 12, v112
	v_mov_b32_e32 v113, v5
	v_lshl_add_u64 v[112:113], v[100:101], 0, v[112:113]
	global_load_dword v148, v[112:113], off
	v_mov_b32_e32 v113, v5
	v_or_b32_e32 v112, s1, v89
	v_lshlrev_b32_e32 v112, 12, v112
	v_lshl_add_u64 v[112:113], v[100:101], 0, v[112:113]
	global_load_dword v150, v[112:113], off
	v_or_b32_e32 v112, s1, v91
	v_lshlrev_b32_e32 v112, 12, v112
	v_mov_b32_e32 v113, v5
	v_lshl_add_u64 v[112:113], v[100:101], 0, v[112:113]
	global_load_dword v151, v[112:113], off
	v_mov_b32_e32 v113, v5
	v_or_b32_e32 v112, s1, v93
	v_lshlrev_b32_e32 v112, 12, v112
	v_lshl_add_u64 v[112:113], v[100:101], 0, v[112:113]
	global_load_dword v152, v[112:113], off
	v_or_b32_e32 v112, s1, v95
	v_lshlrev_b32_e32 v112, 12, v112
	v_mov_b32_e32 v113, v5
	v_lshl_add_u64 v[112:113], v[100:101], 0, v[112:113]
	global_load_dword v153, v[112:113], off
	v_or_b32_e32 v112, s1, v97
	v_lshlrev_b32_e32 v112, 12, v112
	v_mov_b32_e32 v113, v5
	v_lshl_add_u64 v[112:113], v[100:101], 0, v[112:113]
	global_load_dword v154, v[112:113], off
	v_or_b32_e32 v112, s1, v99
	v_lshlrev_b32_e32 v112, 12, v112
	v_mov_b32_e32 v113, v5
	v_lshl_add_u64 v[112:113], v[100:101], 0, v[112:113]
	global_load_dword v155, v[112:113], off
	v_mov_b32_e32 v113, v5
	v_or_b32_e32 v112, s1, v102
	v_lshlrev_b32_e32 v112, 12, v112
	v_lshl_add_u64 v[112:113], v[100:101], 0, v[112:113]
	global_load_dword v156, v[112:113], off
	v_or_b32_e32 v112, s1, v103
	v_lshlrev_b32_e32 v112, 12, v112
	v_mov_b32_e32 v113, v5
	v_lshl_add_u64 v[112:113], v[100:101], 0, v[112:113]
	global_load_dword v157, v[112:113], off
	v_mov_b32_e32 v113, v5
	v_or_b32_e32 v112, s1, v104
	v_lshlrev_b32_e32 v112, 12, v112
	v_lshl_add_u64 v[112:113], v[100:101], 0, v[112:113]
	global_load_dword v158, v[112:113], off
	v_or_b32_e32 v112, s1, v105
	v_lshlrev_b32_e32 v112, 12, v112
	v_mov_b32_e32 v113, v5
	v_lshl_add_u64 v[112:113], v[100:101], 0, v[112:113]
	global_load_dword v159, v[112:113], off
	v_mov_b32_e32 v113, v5
	v_or_b32_e32 v112, s1, v106
	v_lshlrev_b32_e32 v112, 12, v112
	v_lshl_add_u64 v[112:113], v[100:101], 0, v[112:113]
	global_load_dword v160, v[112:113], off
	v_or_b32_e32 v112, s1, v107
	v_lshlrev_b32_e32 v112, 12, v112
	v_mov_b32_e32 v113, v5
	v_lshl_add_u64 v[100:101], v[100:101], 0, v[112:113]
	global_load_dword v161, v[100:101], off
	s_waitcnt vmcnt(0)
	v_add_u32_e32 v115, v19, v37
	s_lshl_b32 s10, s1, 1
	ds_write2_b32 v115, v125, v128 offset1:66
	ds_write2_b32 v115, v130, v131 offset0:132 offset1:198
	v_add_u32_e32 v113, 0x400, v115
	v_add_u32_e32 v115, v19, v51
	ds_write2_b32 v113, v132, v133 offset0:8 offset1:74
	ds_write2_b32 v115, v134, v135 offset1:66
	ds_write2_b32 v115, v136, v137 offset0:132 offset1:198
	v_add_u32_e32 v113, 0x400, v115
	v_add_u32_e32 v115, v19, v65
	ds_write2_b32 v113, v138, v139 offset0:8 offset1:74
	ds_write2_b32 v115, v140, v141 offset1:66
	ds_write2_b32 v115, v142, v143 offset0:132 offset1:198
	v_add_u32_e32 v113, 0x400, v115
	v_add_u32_e32 v115, v19, v75
	ds_write2_b32 v113, v144, v145 offset0:8 offset1:74
	ds_write2_b32 v115, v146, v148 offset1:66
	ds_write2_b32 v115, v150, v151 offset0:132 offset1:198
	v_add_u32_e32 v113, 0x400, v115
	v_add_u32_e32 v115, v19, v77
	ds_write2_b32 v113, v152, v153 offset0:8 offset1:74
	ds_write2_b32 v115, v154, v155 offset1:66
	ds_write2_b32 v115, v156, v157 offset0:132 offset1:198
	v_add_u32_e32 v115, 0x400, v115
	ds_write2_b32 v115, v158, v159 offset0:8 offset1:74
	ds_write2_b32 v115, v160, v161 offset0:140 offset1:206
	s_waitcnt lgkmcnt(0)
	ds_read2_b32 v[112:113], v81 offset1:33
	s_waitcnt lgkmcnt(0)
	v_cvt_pk_bf16_f32 v112, v112, v113
	ds_read2_b32 v[114:115], v81 offset0:66 offset1:99
	s_waitcnt lgkmcnt(0)
	v_cvt_pk_bf16_f32 v113, v114, v115
	ds_read2_b32 v[114:115], v81 offset0:132 offset1:165
	s_waitcnt lgkmcnt(0)
	v_cvt_pk_bf16_f32 v114, v114, v115
	ds_read2_b32 v[116:117], v81 offset0:198 offset1:231
	s_waitcnt lgkmcnt(0)
	v_cvt_pk_bf16_f32 v115, v116, v117
	v_or_b32_e32 v116, s0, v79
	v_lshl_add_u64 v[100:101], v[16:17], 0, s[10:11]
	v_lshlrev_b32_e32 v116, 11, v116
	v_mov_b32_e32 v117, v5
	v_lshl_add_u64 v[116:117], v[100:101], 0, v[116:117]
	global_store_dwordx4 v[116:117], v[112:115], off
	ds_read2_b32 v[112:113], v81 offset0:8 offset1:41
	s_waitcnt lgkmcnt(0)
	v_cvt_pk_bf16_f32 v112, v112, v113
	ds_read2_b32 v[114:115], v81 offset0:74 offset1:107
	s_waitcnt lgkmcnt(0)
	v_cvt_pk_bf16_f32 v113, v114, v115
	ds_read2_b32 v[114:115], v81 offset0:140 offset1:173
	s_waitcnt lgkmcnt(0)
	v_cvt_pk_bf16_f32 v114, v114, v115
	ds_read2_b32 v[116:117], v81 offset0:206 offset1:239
	s_waitcnt lgkmcnt(0)
	v_cvt_pk_bf16_f32 v115, v116, v117
	v_or_b32_e32 v116, s0, v108
	v_lshlrev_b32_e32 v116, 11, v116
	v_mov_b32_e32 v117, v5
	v_lshl_add_u64 v[116:117], v[100:101], 0, v[116:117]
	global_store_dwordx4 v[116:117], v[112:115], off
	ds_read2_b32 v[112:113], v81 offset0:16 offset1:49
	s_waitcnt lgkmcnt(0)
	v_cvt_pk_bf16_f32 v112, v112, v113
	ds_read2_b32 v[114:115], v81 offset0:82 offset1:115
	s_waitcnt lgkmcnt(0)
	v_cvt_pk_bf16_f32 v113, v114, v115
	ds_read2_b32 v[114:115], v81 offset0:148 offset1:181
	s_waitcnt lgkmcnt(0)
	v_cvt_pk_bf16_f32 v114, v114, v115
	ds_read2_b32 v[116:117], v81 offset0:214 offset1:247
	s_waitcnt lgkmcnt(0)
	v_cvt_pk_bf16_f32 v115, v116, v117
	v_or_b32_e32 v116, s0, v109
	v_lshlrev_b32_e32 v116, 11, v116
	v_mov_b32_e32 v117, v5
	v_lshl_add_u64 v[116:117], v[100:101], 0, v[116:117]
	global_store_dwordx4 v[116:117], v[112:115], off
	ds_read2_b32 v[112:113], v81 offset0:24 offset1:57
	s_waitcnt lgkmcnt(0)
	v_cvt_pk_bf16_f32 v112, v112, v113
	ds_read2_b32 v[114:115], v81 offset0:90 offset1:123
	s_waitcnt lgkmcnt(0)
	v_cvt_pk_bf16_f32 v113, v114, v115
	ds_read2_b32 v[114:115], v81 offset0:156 offset1:189
	s_waitcnt lgkmcnt(0)
	v_cvt_pk_bf16_f32 v114, v114, v115
	ds_read2_b32 v[116:117], v81 offset0:222 offset1:255
	s_waitcnt lgkmcnt(0)
	v_cvt_pk_bf16_f32 v115, v116, v117
	v_or_b32_e32 v116, s0, v110
	v_lshlrev_b32_e32 v116, 11, v116
	v_mov_b32_e32 v117, v5
	v_lshl_add_u64 v[100:101], v[100:101], 0, v[116:117]
	global_store_dwordx4 v[100:101], v[112:115], off
	s_waitcnt lgkmcnt(0)

.LBB0_26:
	s_andn2_b64 vcc, exec, s[0:1]
	s_cbranch_vccnz .LBB0_28
	s_add_i32 s10, s21, 0xfffeec00
	v_lshl_add_u64 v[100:101], s[10:11], 2, v[20:21]
	v_lshlrev_b32_e32 v112, 2, v36
	v_mov_b32_e32 v113, v5
	v_lshl_add_u64 v[112:113], v[100:101], 0, v[112:113]
	global_load_dword v125, v[112:113], off
	v_lshlrev_b32_e32 v112, 2, v38
	v_mov_b32_e32 v113, v5
	v_lshl_add_u64 v[112:113], v[100:101], 0, v[112:113]
	global_load_dword v128, v[112:113], off
	v_mov_b32_e32 v113, v5
	v_lshlrev_b32_e32 v112, 2, v40
	v_lshl_add_u64 v[112:113], v[100:101], 0, v[112:113]
	global_load_dword v130, v[112:113], off
	v_lshlrev_b32_e32 v112, 2, v42
	v_mov_b32_e32 v113, v5
	v_lshl_add_u64 v[112:113], v[100:101], 0, v[112:113]
	global_load_dword v131, v[112:113], off
	v_mov_b32_e32 v113, v5
	v_lshlrev_b32_e32 v112, 2, v44
	v_lshl_add_u64 v[112:113], v[100:101], 0, v[112:113]
	global_load_dword v132, v[112:113], off
	v_lshlrev_b32_e32 v112, 2, v46
	v_mov_b32_e32 v113, v5
	v_lshl_add_u64 v[112:113], v[100:101], 0, v[112:113]
	global_load_dword v133, v[112:113], off
	v_lshlrev_b32_e32 v112, 2, v48
	v_mov_b32_e32 v113, v5
	v_lshl_add_u64 v[112:113], v[100:101], 0, v[112:113]
	global_load_dword v134, v[112:113], off
	v_lshlrev_b32_e32 v112, 2, v50
	v_mov_b32_e32 v113, v5
	v_lshl_add_u64 v[112:113], v[100:101], 0, v[112:113]
	global_load_dword v135, v[112:113], off
	v_mov_b32_e32 v113, v5
	v_lshlrev_b32_e32 v112, 2, v52
	v_lshl_add_u64 v[112:113], v[100:101], 0, v[112:113]
	global_load_dword v136, v[112:113], off
	v_lshlrev_b32_e32 v112, 2, v54
	v_mov_b32_e32 v113, v5
	v_lshl_add_u64 v[112:113], v[100:101], 0, v[112:113]
	global_load_dword v137, v[112:113], off
	v_mov_b32_e32 v113, v5
	v_lshlrev_b32_e32 v112, 2, v56
	v_lshl_add_u64 v[112:113], v[100:101], 0, v[112:113]
	global_load_dword v138, v[112:113], off
	v_lshlrev_b32_e32 v112, 2, v58
	v_mov_b32_e32 v113, v5
	v_lshl_add_u64 v[112:113], v[100:101], 0, v[112:113]
	global_load_dword v139, v[112:113], off
	v_lshlrev_b32_e32 v112, 2, v60
	v_mov_b32_e32 v113, v5
	v_lshl_add_u64 v[112:113], v[100:101], 0, v[112:113]
	global_load_dword v140, v[112:113], off
	v_lshlrev_b32_e32 v112, 2, v62
	v_mov_b32_e32 v113, v5
	v_lshl_add_u64 v[112:113], v[100:101], 0, v[112:113]
	global_load_dword v141, v[112:113], off
	v_mov_b32_e32 v113, v5
	v_lshlrev_b32_e32 v112, 2, v64
	v_lshl_add_u64 v[112:113], v[100:101], 0, v[112:113]
	global_load_dword v142, v[112:113], off
	v_lshlrev_b32_e32 v112, 2, v66
	v_mov_b32_e32 v113, v5
	v_lshl_add_u64 v[112:113], v[100:101], 0, v[112:113]
	global_load_dword v143, v[112:113], off
	v_mov_b32_e32 v113, v5
	v_lshlrev_b32_e32 v112, 2, v68
	v_lshl_add_u64 v[112:113], v[100:101], 0, v[112:113]
	global_load_dword v144, v[112:113], off
	v_lshlrev_b32_e32 v112, 2, v70
	v_mov_b32_e32 v113, v5
	v_lshl_add_u64 v[112:113], v[100:101], 0, v[112:113]
	global_load_dword v145, v[112:113], off
	v_lshlrev_b32_e32 v112, 2, v72
	v_mov_b32_e32 v113, v5
	v_lshl_add_u64 v[112:113], v[100:101], 0, v[112:113]
	global_load_dword v146, v[112:113], off
	v_lshlrev_b32_e32 v112, 2, v74
	v_mov_b32_e32 v113, v5
	v_lshl_add_u64 v[112:113], v[100:101], 0, v[112:113]
	global_load_dword v148, v[112:113], off
	v_mov_b32_e32 v113, v5
	v_lshlrev_b32_e32 v112, 2, v76
	v_lshl_add_u64 v[112:113], v[100:101], 0, v[112:113]
	global_load_dword v150, v[112:113], off
	v_lshlrev_b32_e32 v112, 2, v78
	v_mov_b32_e32 v113, v5
	v_lshl_add_u64 v[112:113], v[100:101], 0, v[112:113]
	global_load_dword v151, v[112:113], off
	v_mov_b32_e32 v113, v5
	v_lshlrev_b32_e32 v112, 2, v80
	v_lshl_add_u64 v[112:113], v[100:101], 0, v[112:113]
	global_load_dword v152, v[112:113], off
	v_lshlrev_b32_e32 v112, 2, v82
	v_mov_b32_e32 v113, v5
	v_lshl_add_u64 v[112:113], v[100:101], 0, v[112:113]
	global_load_dword v153, v[112:113], off
	v_lshlrev_b32_e32 v112, 2, v84
	v_mov_b32_e32 v113, v5
	v_lshl_add_u64 v[112:113], v[100:101], 0, v[112:113]
	global_load_dword v154, v[112:113], off
	v_lshlrev_b32_e32 v112, 2, v86
	v_mov_b32_e32 v113, v5
	v_lshl_add_u64 v[112:113], v[100:101], 0, v[112:113]
	global_load_dword v155, v[112:113], off
	v_mov_b32_e32 v113, v5
	v_lshlrev_b32_e32 v112, 2, v88
	v_lshl_add_u64 v[112:113], v[100:101], 0, v[112:113]
	global_load_dword v156, v[112:113], off
	v_lshlrev_b32_e32 v112, 2, v90
	v_mov_b32_e32 v113, v5
	v_lshl_add_u64 v[112:113], v[100:101], 0, v[112:113]
	global_load_dword v157, v[112:113], off
	v_mov_b32_e32 v113, v5
	v_lshlrev_b32_e32 v112, 2, v92
	v_lshl_add_u64 v[112:113], v[100:101], 0, v[112:113]
	global_load_dword v158, v[112:113], off
	v_lshlrev_b32_e32 v112, 2, v94
	v_mov_b32_e32 v113, v5
	v_lshl_add_u64 v[112:113], v[100:101], 0, v[112:113]
	global_load_dword v159, v[112:113], off
	v_mov_b32_e32 v113, v5
	v_lshlrev_b32_e32 v112, 2, v96
	v_lshl_add_u64 v[112:113], v[100:101], 0, v[112:113]
	global_load_dword v160, v[112:113], off
	v_lshlrev_b32_e32 v112, 2, v98
	v_mov_b32_e32 v113, v5
	v_lshl_add_u64 v[100:101], v[100:101], 0, v[112:113]
	global_load_dword v161, v[100:101], off
	s_waitcnt vmcnt(0)
	v_add_u32_e32 v115, v19, v37
	v_add_u32_e32 v116, s21, v79
	ds_write2_b32 v115, v125, v128 offset1:66
	ds_write2_b32 v115, v130, v131 offset0:132 offset1:198
	v_add_u32_e32 v113, 0x400, v115
	v_add_u32_e32 v115, v19, v51
	ds_write2_b32 v113, v132, v133 offset0:8 offset1:74
	ds_write2_b32 v115, v134, v135 offset1:66
	ds_write2_b32 v115, v136, v137 offset0:132 offset1:198
	v_add_u32_e32 v113, 0x400, v115
	v_add_u32_e32 v115, v19, v65
	ds_write2_b32 v113, v138, v139 offset0:8 offset1:74
	ds_write2_b32 v115, v140, v141 offset1:66
	ds_write2_b32 v115, v142, v143 offset0:132 offset1:198
	v_add_u32_e32 v113, 0x400, v115
	v_add_u32_e32 v115, v19, v75
	ds_write2_b32 v113, v144, v145 offset0:8 offset1:74
	ds_write2_b32 v115, v146, v148 offset1:66
	ds_write2_b32 v115, v150, v151 offset0:132 offset1:198
	v_add_u32_e32 v113, 0x400, v115
	v_add_u32_e32 v115, v19, v77
	ds_write2_b32 v113, v152, v153 offset0:8 offset1:74
	ds_write2_b32 v115, v154, v155 offset1:66
	ds_write2_b32 v115, v156, v157 offset0:132 offset1:198
	v_add_u32_e32 v115, 0x400, v115
	ds_write2_b32 v115, v158, v159 offset0:8 offset1:74
	ds_write2_b32 v115, v160, v161 offset0:140 offset1:206
	s_waitcnt lgkmcnt(0)
	ds_read2_b32 v[100:101], v81 offset1:33
	s_waitcnt lgkmcnt(0)
	v_cvt_pk_bf16_f32 v112, v100, v101
	ds_read2_b32 v[100:101], v81 offset0:66 offset1:99
	s_waitcnt lgkmcnt(0)
	v_cvt_pk_bf16_f32 v113, v100, v101
	ds_read2_b32 v[100:101], v81 offset0:132 offset1:165
	s_waitcnt lgkmcnt(0)
	v_cvt_pk_bf16_f32 v114, v100, v101
	ds_read2_b32 v[100:101], v81 offset0:198 offset1:231
	s_waitcnt lgkmcnt(0)
	v_cvt_pk_bf16_f32 v115, v100, v101
	v_add_u32_e32 v100, 0xfffef000, v116
	v_mov_b32_e32 v101, v5
	v_lshlrev_b64 v[100:101], 8, v[100:101]
	v_lshl_add_u64 v[100:101], v[22:23], 0, v[100:101]
	global_store_dwordx4 v[100:101], v[112:115], off
	ds_read2_b32 v[100:101], v81 offset0:8 offset1:41
	s_waitcnt lgkmcnt(0)
	v_cvt_pk_bf16_f32 v112, v100, v101
	ds_read2_b32 v[100:101], v81 offset0:74 offset1:107
	s_waitcnt lgkmcnt(0)
	v_cvt_pk_bf16_f32 v113, v100, v101
	ds_read2_b32 v[100:101], v81 offset0:140 offset1:173
	s_waitcnt lgkmcnt(0)
	v_cvt_pk_bf16_f32 v114, v100, v101
	ds_read2_b32 v[100:101], v81 offset0:206 offset1:239
	s_waitcnt lgkmcnt(0)
	v_cvt_pk_bf16_f32 v115, v100, v101
	v_add_u32_e32 v100, 0xfffef008, v116
	v_mov_b32_e32 v101, v5
	v_lshlrev_b64 v[100:101], 8, v[100:101]
	v_lshl_add_u64 v[100:101], v[22:23], 0, v[100:101]
	global_store_dwordx4 v[100:101], v[112:115], off
	ds_read2_b32 v[100:101], v81 offset0:16 offset1:49
	s_waitcnt lgkmcnt(0)
	v_cvt_pk_bf16_f32 v112, v100, v101
	ds_read2_b32 v[100:101], v81 offset0:82 offset1:115
	s_waitcnt lgkmcnt(0)
	v_cvt_pk_bf16_f32 v113, v100, v101
	ds_read2_b32 v[100:101], v81 offset0:148 offset1:181
	s_waitcnt lgkmcnt(0)
	v_cvt_pk_bf16_f32 v114, v100, v101
	ds_read2_b32 v[100:101], v81 offset0:214 offset1:247
	s_waitcnt lgkmcnt(0)
	v_cvt_pk_bf16_f32 v115, v100, v101
	v_add_u32_e32 v100, 0xfffef010, v116
	v_mov_b32_e32 v101, v5
	v_lshlrev_b64 v[100:101], 8, v[100:101]
	v_lshl_add_u64 v[100:101], v[22:23], 0, v[100:101]
	global_store_dwordx4 v[100:101], v[112:115], off
	ds_read2_b32 v[100:101], v81 offset0:24 offset1:57
	s_waitcnt lgkmcnt(0)
	v_cvt_pk_bf16_f32 v112, v100, v101
	ds_read2_b32 v[100:101], v81 offset0:90 offset1:123
	s_waitcnt lgkmcnt(0)
	v_cvt_pk_bf16_f32 v113, v100, v101
	ds_read2_b32 v[100:101], v81 offset0:156 offset1:189
	s_waitcnt lgkmcnt(0)
	v_cvt_pk_bf16_f32 v114, v100, v101
	ds_read2_b32 v[100:101], v81 offset0:222 offset1:255
	s_waitcnt lgkmcnt(0)
	v_cvt_pk_bf16_f32 v115, v100, v101
	v_add_u32_e32 v100, 0xfffef018, v116
	v_mov_b32_e32 v101, v5
	v_lshlrev_b64 v[100:101], 8, v[100:101]
	v_lshl_add_u64 v[100:101], v[22:23], 0, v[100:101]
	global_store_dwordx4 v[100:101], v[112:115], off
	s_waitcnt lgkmcnt(0)

.LBB0_29:
	s_andn2_b64 vcc, exec, s[0:1]
	s_cbranch_vccnz .LBB0_31
	s_add_i32 s10, s21, 0xfffef000
	v_lshl_add_u64 v[100:101], s[10:11], 2, v[24:25]
	v_lshlrev_b32_e32 v112, 2, v36
	v_mov_b32_e32 v113, v5
	v_lshl_add_u64 v[112:113], v[100:101], 0, v[112:113]
	global_load_dword v125, v[112:113], off
	v_lshlrev_b32_e32 v112, 2, v38
	v_mov_b32_e32 v113, v5
	v_lshl_add_u64 v[112:113], v[100:101], 0, v[112:113]
	global_load_dword v128, v[112:113], off
	v_mov_b32_e32 v113, v5
	v_lshlrev_b32_e32 v112, 2, v40
	v_lshl_add_u64 v[112:113], v[100:101], 0, v[112:113]
	global_load_dword v130, v[112:113], off
	v_lshlrev_b32_e32 v112, 2, v42
	v_mov_b32_e32 v113, v5
	v_lshl_add_u64 v[112:113], v[100:101], 0, v[112:113]
	global_load_dword v131, v[112:113], off
	v_mov_b32_e32 v113, v5
	v_lshlrev_b32_e32 v112, 2, v44
	v_lshl_add_u64 v[112:113], v[100:101], 0, v[112:113]
	global_load_dword v132, v[112:113], off
	v_lshlrev_b32_e32 v112, 2, v46
	v_mov_b32_e32 v113, v5
	v_lshl_add_u64 v[112:113], v[100:101], 0, v[112:113]
	global_load_dword v133, v[112:113], off
	v_lshlrev_b32_e32 v112, 2, v48
	v_mov_b32_e32 v113, v5
	v_lshl_add_u64 v[112:113], v[100:101], 0, v[112:113]
	global_load_dword v134, v[112:113], off
	v_lshlrev_b32_e32 v112, 2, v50
	v_mov_b32_e32 v113, v5
	v_lshl_add_u64 v[112:113], v[100:101], 0, v[112:113]
	global_load_dword v135, v[112:113], off
	v_mov_b32_e32 v113, v5
	v_lshlrev_b32_e32 v112, 2, v52
	v_lshl_add_u64 v[112:113], v[100:101], 0, v[112:113]
	global_load_dword v136, v[112:113], off
	v_lshlrev_b32_e32 v112, 2, v54
	v_mov_b32_e32 v113, v5
	v_lshl_add_u64 v[112:113], v[100:101], 0, v[112:113]
	global_load_dword v137, v[112:113], off
	v_mov_b32_e32 v113, v5
	v_lshlrev_b32_e32 v112, 2, v56
	v_lshl_add_u64 v[112:113], v[100:101], 0, v[112:113]
	global_load_dword v138, v[112:113], off
	v_lshlrev_b32_e32 v112, 2, v58
	v_mov_b32_e32 v113, v5
	v_lshl_add_u64 v[112:113], v[100:101], 0, v[112:113]
	global_load_dword v139, v[112:113], off
	v_lshlrev_b32_e32 v112, 2, v60
	v_mov_b32_e32 v113, v5
	v_lshl_add_u64 v[112:113], v[100:101], 0, v[112:113]
	global_load_dword v140, v[112:113], off
	v_lshlrev_b32_e32 v112, 2, v62
	v_mov_b32_e32 v113, v5
	v_lshl_add_u64 v[112:113], v[100:101], 0, v[112:113]
	global_load_dword v141, v[112:113], off
	v_mov_b32_e32 v113, v5
	v_lshlrev_b32_e32 v112, 2, v64
	v_lshl_add_u64 v[112:113], v[100:101], 0, v[112:113]
	global_load_dword v142, v[112:113], off
	v_lshlrev_b32_e32 v112, 2, v66
	v_mov_b32_e32 v113, v5
	v_lshl_add_u64 v[112:113], v[100:101], 0, v[112:113]
	global_load_dword v143, v[112:113], off
	v_mov_b32_e32 v113, v5
	v_lshlrev_b32_e32 v112, 2, v68
	v_lshl_add_u64 v[112:113], v[100:101], 0, v[112:113]
	global_load_dword v144, v[112:113], off
	v_lshlrev_b32_e32 v112, 2, v70
	v_mov_b32_e32 v113, v5
	v_lshl_add_u64 v[112:113], v[100:101], 0, v[112:113]
	global_load_dword v145, v[112:113], off
	v_lshlrev_b32_e32 v112, 2, v72
	v_mov_b32_e32 v113, v5
	v_lshl_add_u64 v[112:113], v[100:101], 0, v[112:113]
	global_load_dword v146, v[112:113], off
	v_lshlrev_b32_e32 v112, 2, v74
	v_mov_b32_e32 v113, v5
	v_lshl_add_u64 v[112:113], v[100:101], 0, v[112:113]
	global_load_dword v148, v[112:113], off
	v_mov_b32_e32 v113, v5
	v_lshlrev_b32_e32 v112, 2, v76
	v_lshl_add_u64 v[112:113], v[100:101], 0, v[112:113]
	global_load_dword v150, v[112:113], off
	v_lshlrev_b32_e32 v112, 2, v78
	v_mov_b32_e32 v113, v5
	v_lshl_add_u64 v[112:113], v[100:101], 0, v[112:113]
	global_load_dword v151, v[112:113], off
	v_mov_b32_e32 v113, v5
	v_lshlrev_b32_e32 v112, 2, v80
	v_lshl_add_u64 v[112:113], v[100:101], 0, v[112:113]
	global_load_dword v152, v[112:113], off
	v_lshlrev_b32_e32 v112, 2, v82
	v_mov_b32_e32 v113, v5
	v_lshl_add_u64 v[112:113], v[100:101], 0, v[112:113]
	global_load_dword v153, v[112:113], off
	v_lshlrev_b32_e32 v112, 2, v84
	v_mov_b32_e32 v113, v5
	v_lshl_add_u64 v[112:113], v[100:101], 0, v[112:113]
	global_load_dword v154, v[112:113], off
	v_lshlrev_b32_e32 v112, 2, v86
	v_mov_b32_e32 v113, v5
	v_lshl_add_u64 v[112:113], v[100:101], 0, v[112:113]
	global_load_dword v155, v[112:113], off
	v_mov_b32_e32 v113, v5
	v_lshlrev_b32_e32 v112, 2, v88
	v_lshl_add_u64 v[112:113], v[100:101], 0, v[112:113]
	global_load_dword v156, v[112:113], off
	v_lshlrev_b32_e32 v112, 2, v90
	v_mov_b32_e32 v113, v5
	v_lshl_add_u64 v[112:113], v[100:101], 0, v[112:113]
	global_load_dword v157, v[112:113], off
	v_mov_b32_e32 v113, v5
	v_lshlrev_b32_e32 v112, 2, v92
	v_lshl_add_u64 v[112:113], v[100:101], 0, v[112:113]
	global_load_dword v158, v[112:113], off
	v_lshlrev_b32_e32 v112, 2, v94
	v_mov_b32_e32 v113, v5
	v_lshl_add_u64 v[112:113], v[100:101], 0, v[112:113]
	global_load_dword v159, v[112:113], off
	v_mov_b32_e32 v113, v5
	v_lshlrev_b32_e32 v112, 2, v96
	v_lshl_add_u64 v[112:113], v[100:101], 0, v[112:113]
	global_load_dword v160, v[112:113], off
	v_lshlrev_b32_e32 v112, 2, v98
	v_mov_b32_e32 v113, v5
	v_lshl_add_u64 v[100:101], v[100:101], 0, v[112:113]
	global_load_dword v161, v[100:101], off
	s_waitcnt vmcnt(0)
	v_add_u32_e32 v115, v19, v37
	v_add_u32_e32 v116, s21, v79
	ds_write2_b32 v115, v125, v128 offset1:66
	ds_write2_b32 v115, v130, v131 offset0:132 offset1:198
	v_add_u32_e32 v113, 0x400, v115
	v_add_u32_e32 v115, v19, v51
	ds_write2_b32 v113, v132, v133 offset0:8 offset1:74
	ds_write2_b32 v115, v134, v135 offset1:66
	ds_write2_b32 v115, v136, v137 offset0:132 offset1:198
	v_add_u32_e32 v113, 0x400, v115
	v_add_u32_e32 v115, v19, v65
	ds_write2_b32 v113, v138, v139 offset0:8 offset1:74
	ds_write2_b32 v115, v140, v141 offset1:66
	ds_write2_b32 v115, v142, v143 offset0:132 offset1:198
	v_add_u32_e32 v113, 0x400, v115
	v_add_u32_e32 v115, v19, v75
	ds_write2_b32 v113, v144, v145 offset0:8 offset1:74
	ds_write2_b32 v115, v146, v148 offset1:66
	ds_write2_b32 v115, v150, v151 offset0:132 offset1:198
	v_add_u32_e32 v113, 0x400, v115
	v_add_u32_e32 v115, v19, v77
	ds_write2_b32 v113, v152, v153 offset0:8 offset1:74
	ds_write2_b32 v115, v154, v155 offset1:66
	ds_write2_b32 v115, v156, v157 offset0:132 offset1:198
	v_add_u32_e32 v115, 0x400, v115
	ds_write2_b32 v115, v158, v159 offset0:8 offset1:74
	ds_write2_b32 v115, v160, v161 offset0:140 offset1:206
	s_waitcnt lgkmcnt(0)
	ds_read2_b32 v[100:101], v81 offset1:33
	s_waitcnt lgkmcnt(0)
	v_cvt_pk_bf16_f32 v112, v100, v101
	ds_read2_b32 v[100:101], v81 offset0:66 offset1:99
	s_waitcnt lgkmcnt(0)
	v_cvt_pk_bf16_f32 v113, v100, v101
	ds_read2_b32 v[100:101], v81 offset0:132 offset1:165
	s_waitcnt lgkmcnt(0)
	v_cvt_pk_bf16_f32 v114, v100, v101
	ds_read2_b32 v[100:101], v81 offset0:198 offset1:231
	s_waitcnt lgkmcnt(0)
	v_cvt_pk_bf16_f32 v115, v100, v101
	v_add_u32_e32 v100, 0xfffef000, v116
	v_mov_b32_e32 v101, v5
	v_lshlrev_b64 v[100:101], 8, v[100:101]
	v_lshl_add_u64 v[100:101], v[26:27], 0, v[100:101]
	global_store_dwordx4 v[100:101], v[112:115], off
	ds_read2_b32 v[100:101], v81 offset0:8 offset1:41
	s_waitcnt lgkmcnt(0)
	v_cvt_pk_bf16_f32 v112, v100, v101
	ds_read2_b32 v[100:101], v81 offset0:74 offset1:107
	s_waitcnt lgkmcnt(0)
	v_cvt_pk_bf16_f32 v113, v100, v101
	ds_read2_b32 v[100:101], v81 offset0:140 offset1:173
	s_waitcnt lgkmcnt(0)
	v_cvt_pk_bf16_f32 v114, v100, v101
	ds_read2_b32 v[100:101], v81 offset0:206 offset1:239
	s_waitcnt lgkmcnt(0)
	v_cvt_pk_bf16_f32 v115, v100, v101
	v_add_u32_e32 v100, 0xfffef008, v116
	v_mov_b32_e32 v101, v5
	v_lshlrev_b64 v[100:101], 8, v[100:101]
	v_lshl_add_u64 v[100:101], v[26:27], 0, v[100:101]
	global_store_dwordx4 v[100:101], v[112:115], off
	ds_read2_b32 v[100:101], v81 offset0:16 offset1:49
	s_waitcnt lgkmcnt(0)
	v_cvt_pk_bf16_f32 v112, v100, v101
	ds_read2_b32 v[100:101], v81 offset0:82 offset1:115
	s_waitcnt lgkmcnt(0)
	v_cvt_pk_bf16_f32 v113, v100, v101
	ds_read2_b32 v[100:101], v81 offset0:148 offset1:181
	s_waitcnt lgkmcnt(0)
	v_cvt_pk_bf16_f32 v114, v100, v101
	ds_read2_b32 v[100:101], v81 offset0:214 offset1:247
	s_waitcnt lgkmcnt(0)
	v_cvt_pk_bf16_f32 v115, v100, v101
	v_add_u32_e32 v100, 0xfffef010, v116
	v_mov_b32_e32 v101, v5
	v_lshlrev_b64 v[100:101], 8, v[100:101]
	v_lshl_add_u64 v[100:101], v[26:27], 0, v[100:101]
	global_store_dwordx4 v[100:101], v[112:115], off
	ds_read2_b32 v[100:101], v81 offset0:24 offset1:57
	s_waitcnt lgkmcnt(0)
	v_cvt_pk_bf16_f32 v112, v100, v101
	ds_read2_b32 v[100:101], v81 offset0:90 offset1:123
	s_waitcnt lgkmcnt(0)
	v_cvt_pk_bf16_f32 v113, v100, v101
	ds_read2_b32 v[100:101], v81 offset0:156 offset1:189
	s_waitcnt lgkmcnt(0)
	v_cvt_pk_bf16_f32 v114, v100, v101
	ds_read2_b32 v[100:101], v81 offset0:222 offset1:255
	s_waitcnt lgkmcnt(0)
	v_cvt_pk_bf16_f32 v115, v100, v101
	v_add_u32_e32 v100, 0xfffef018, v116
	v_mov_b32_e32 v101, v5
	v_lshlrev_b64 v[100:101], 8, v[100:101]
	v_lshl_add_u64 v[100:101], v[26:27], 0, v[100:101]
	global_store_dwordx4 v[100:101], v[112:115], off
	s_waitcnt lgkmcnt(0)

.LBB0_32:
	s_andn2_b64 vcc, exec, s[0:1]
	s_cbranch_vccnz .LBB0_34
	s_add_i32 s0, s21, 0x1400
	s_and_b32 s1, s0, 0x1fc0
	s_and_b32 s0, s21, 32
	s_lshl_b32 s10, s0, 2
	v_or_b32_e32 v114, s1, v3
	v_lshl_add_u64 v[100:101], v[28:29], 0, s[10:11]
	v_lshlrev_b32_e32 v112, 8, v114
	v_mov_b32_e32 v113, v5
	v_lshl_add_u64 v[112:113], v[100:101], 0, v[112:113]
	global_load_dword v125, v[112:113], off
	v_lshlrev_b32_e32 v113, 2, v114
	global_load_dword v128, v113, s[6:7]
	v_or_b32_e32 v116, s1, v39
	v_lshlrev_b32_e32 v112, 8, v116
	v_mov_b32_e32 v113, v5
	v_lshl_add_u64 v[112:113], v[100:101], 0, v[112:113]
	global_load_dword v130, v[112:113], off
	v_lshlrev_b32_e32 v113, 2, v116
	global_load_dword v131, v113, s[6:7]
	v_or_b32_e32 v116, s1, v43
	v_or_b32_e32 v114, s1, v41
	v_lshlrev_b32_e32 v112, 8, v114
	v_mov_b32_e32 v113, v5
	v_lshl_add_u64 v[112:113], v[100:101], 0, v[112:113]
	global_load_dword v132, v[112:113], off
	v_lshlrev_b32_e32 v113, 2, v114
	global_load_dword v133, v113, s[6:7]
	v_lshlrev_b32_e32 v112, 8, v116
	v_mov_b32_e32 v113, v5
	v_lshl_add_u64 v[112:113], v[100:101], 0, v[112:113]
	global_load_dword v134, v[112:113], off
	v_lshlrev_b32_e32 v113, 2, v116
	global_load_dword v135, v113, s[6:7]
	v_or_b32_e32 v116, s1, v47
	v_or_b32_e32 v114, s1, v45
	v_lshlrev_b32_e32 v112, 8, v114
	v_mov_b32_e32 v113, v5
	v_lshl_add_u64 v[112:113], v[100:101], 0, v[112:113]
	global_load_dword v136, v[112:113], off
	v_lshlrev_b32_e32 v113, 2, v114
	global_load_dword v137, v113, s[6:7]
	v_lshlrev_b32_e32 v112, 8, v116
	v_mov_b32_e32 v113, v5
	v_lshl_add_u64 v[112:113], v[100:101], 0, v[112:113]
	global_load_dword v138, v[112:113], off
	v_lshlrev_b32_e32 v113, 2, v116
	global_load_dword v139, v113, s[6:7]
	v_or_b32_e32 v116, s1, v53
	v_or_b32_e32 v114, s1, v49
	v_lshlrev_b32_e32 v112, 8, v114
	v_mov_b32_e32 v113, v5
	v_lshl_add_u64 v[112:113], v[100:101], 0, v[112:113]
	global_load_dword v140, v[112:113], off
	v_lshlrev_b32_e32 v113, 2, v114
	global_load_dword v141, v113, s[6:7]
	v_lshlrev_b32_e32 v112, 8, v116
	v_mov_b32_e32 v113, v5
	v_lshl_add_u64 v[112:113], v[100:101], 0, v[112:113]
	global_load_dword v142, v[112:113], off
	v_lshlrev_b32_e32 v113, 2, v116
	global_load_dword v143, v113, s[6:7]
	v_or_b32_e32 v116, s1, v57
	v_or_b32_e32 v114, s1, v55
	v_lshlrev_b32_e32 v112, 8, v114
	v_mov_b32_e32 v113, v5
	v_lshl_add_u64 v[112:113], v[100:101], 0, v[112:113]
	global_load_dword v144, v[112:113], off
	v_lshlrev_b32_e32 v113, 2, v114
	global_load_dword v145, v113, s[6:7]
	v_lshlrev_b32_e32 v112, 8, v116
	v_mov_b32_e32 v113, v5
	v_lshl_add_u64 v[112:113], v[100:101], 0, v[112:113]
	global_load_dword v146, v[112:113], off
	v_lshlrev_b32_e32 v113, 2, v116
	global_load_dword v148, v113, s[6:7]
	v_or_b32_e32 v116, s1, v61
	v_or_b32_e32 v114, s1, v59
	v_lshlrev_b32_e32 v112, 8, v114
	v_mov_b32_e32 v113, v5
	v_lshl_add_u64 v[112:113], v[100:101], 0, v[112:113]
	global_load_dword v150, v[112:113], off
	v_lshlrev_b32_e32 v113, 2, v114
	global_load_dword v151, v113, s[6:7]
	v_lshlrev_b32_e32 v112, 8, v116
	v_mov_b32_e32 v113, v5
	v_lshl_add_u64 v[112:113], v[100:101], 0, v[112:113]
	global_load_dword v152, v[112:113], off
	v_lshlrev_b32_e32 v113, 2, v116
	global_load_dword v153, v113, s[6:7]
	v_or_b32_e32 v116, s1, v67
	v_or_b32_e32 v114, s1, v63
	v_lshlrev_b32_e32 v112, 8, v114
	v_mov_b32_e32 v113, v5
	v_lshl_add_u64 v[112:113], v[100:101], 0, v[112:113]
	global_load_dword v154, v[112:113], off
	v_lshlrev_b32_e32 v113, 2, v114
	global_load_dword v155, v113, s[6:7]
	v_lshlrev_b32_e32 v112, 8, v116
	v_mov_b32_e32 v113, v5
	v_lshl_add_u64 v[112:113], v[100:101], 0, v[112:113]
	global_load_dword v156, v[112:113], off
	v_lshlrev_b32_e32 v113, 2, v116
	global_load_dword v157, v113, s[6:7]
	v_or_b32_e32 v116, s1, v71
	v_or_b32_e32 v114, s1, v69
	v_lshlrev_b32_e32 v112, 8, v114
	v_mov_b32_e32 v113, v5
	v_lshl_add_u64 v[112:113], v[100:101], 0, v[112:113]
	global_load_dword v158, v[112:113], off
	v_lshlrev_b32_e32 v113, 2, v114
	global_load_dword v159, v113, s[6:7]
	v_lshlrev_b32_e32 v112, 8, v116
	v_mov_b32_e32 v113, v5
	v_lshl_add_u64 v[112:113], v[100:101], 0, v[112:113]
	global_load_dword v160, v[112:113], off
	v_lshlrev_b32_e32 v113, 2, v116
	global_load_dword v161, v113, s[6:7]
	v_or_b32_e32 v116, s1, v83
	v_or_b32_e32 v114, s1, v73
	v_lshlrev_b32_e32 v112, 8, v114
	v_mov_b32_e32 v113, v5
	v_lshl_add_u64 v[112:113], v[100:101], 0, v[112:113]
	global_load_dword v162, v[112:113], off
	v_lshlrev_b32_e32 v113, 2, v114
	global_load_dword v163, v113, s[6:7]
	v_lshlrev_b32_e32 v112, 8, v116
	v_mov_b32_e32 v113, v5
	v_lshl_add_u64 v[112:113], v[100:101], 0, v[112:113]
	global_load_dword v164, v[112:113], off
	v_lshlrev_b32_e32 v113, 2, v116
	global_load_dword v165, v113, s[6:7]
	v_or_b32_e32 v116, s1, v87
	v_or_b32_e32 v114, s1, v85
	v_lshlrev_b32_e32 v112, 8, v114
	v_mov_b32_e32 v113, v5
	v_lshl_add_u64 v[112:113], v[100:101], 0, v[112:113]
	global_load_dword v166, v[112:113], off
	v_lshlrev_b32_e32 v113, 2, v114
	global_load_dword v168, v113, s[6:7]
	v_lshlrev_b32_e32 v112, 8, v116
	v_mov_b32_e32 v113, v5
	v_lshl_add_u64 v[112:113], v[100:101], 0, v[112:113]
	global_load_dword v170, v[112:113], off
	v_lshlrev_b32_e32 v113, 2, v116
	global_load_dword v171, v113, s[6:7]
	v_or_b32_e32 v116, s1, v91
	v_or_b32_e32 v114, s1, v89
	v_lshlrev_b32_e32 v112, 8, v114
	v_mov_b32_e32 v113, v5
	v_lshl_add_u64 v[112:113], v[100:101], 0, v[112:113]
	global_load_dword v172, v[112:113], off
	v_lshlrev_b32_e32 v113, 2, v114
	global_load_dword v173, v113, s[6:7]
	v_lshlrev_b32_e32 v112, 8, v116
	v_mov_b32_e32 v113, v5
	v_lshl_add_u64 v[112:113], v[100:101], 0, v[112:113]
	global_load_dword v174, v[112:113], off
	v_lshlrev_b32_e32 v113, 2, v116
	global_load_dword v176, v113, s[6:7]
	v_or_b32_e32 v116, s1, v95
	v_or_b32_e32 v114, s1, v93
	v_lshlrev_b32_e32 v112, 8, v114
	v_mov_b32_e32 v113, v5
	v_lshl_add_u64 v[112:113], v[100:101], 0, v[112:113]
	global_load_dword v177, v[112:113], off
	v_lshlrev_b32_e32 v113, 2, v114
	global_load_dword v178, v113, s[6:7]
	v_lshlrev_b32_e32 v112, 8, v116
	v_mov_b32_e32 v113, v5
	v_lshl_add_u64 v[112:113], v[100:101], 0, v[112:113]
	global_load_dword v179, v[112:113], off
	v_lshlrev_b32_e32 v113, 2, v116
	global_load_dword v180, v113, s[6:7]
	v_or_b32_e32 v116, s1, v99
	v_or_b32_e32 v114, s1, v97
	v_lshlrev_b32_e32 v112, 8, v114
	v_mov_b32_e32 v113, v5
	v_lshl_add_u64 v[112:113], v[100:101], 0, v[112:113]
	s_waitcnt vmcnt(16)
	global_load_dword v181, v[112:113], off
	v_lshlrev_b32_e32 v113, 2, v114
	global_load_dword v182, v113, s[6:7]
	v_lshlrev_b32_e32 v112, 8, v116
	v_mov_b32_e32 v113, v5
	v_lshl_add_u64 v[112:113], v[100:101], 0, v[112:113]
	global_load_dword v183, v[112:113], off
	v_lshlrev_b32_e32 v113, 2, v116
	global_load_dword v184, v113, s[6:7]
	v_or_b32_e32 v116, s1, v103
	v_or_b32_e32 v114, s1, v102
	v_lshlrev_b32_e32 v112, 8, v114
	v_mov_b32_e32 v113, v5
	v_lshl_add_u64 v[112:113], v[100:101], 0, v[112:113]
	global_load_dword v185, v[112:113], off
	v_lshlrev_b32_e32 v113, 2, v114
	global_load_dword v186, v113, s[6:7]
	v_lshlrev_b32_e32 v112, 8, v116
	v_mov_b32_e32 v113, v5
	v_lshl_add_u64 v[112:113], v[100:101], 0, v[112:113]
	global_load_dword v187, v[112:113], off
	v_lshlrev_b32_e32 v113, 2, v116
	global_load_dword v188, v113, s[6:7]
	v_or_b32_e32 v116, s1, v105
	v_or_b32_e32 v114, s1, v104
	v_lshlrev_b32_e32 v112, 8, v114
	v_mov_b32_e32 v113, v5
	v_lshl_add_u64 v[112:113], v[100:101], 0, v[112:113]
	global_load_dword v189, v[112:113], off
	v_lshlrev_b32_e32 v113, 2, v114
	global_load_dword v190, v113, s[6:7]
	v_lshlrev_b32_e32 v112, 8, v116
	v_mov_b32_e32 v113, v5
	v_lshl_add_u64 v[112:113], v[100:101], 0, v[112:113]
	global_load_dword v191, v[112:113], off
	v_lshlrev_b32_e32 v113, 2, v116
	global_load_dword v192, v113, s[6:7]
	v_or_b32_e32 v116, s1, v107
	v_or_b32_e32 v114, s1, v106
	v_lshlrev_b32_e32 v112, 8, v114
	v_mov_b32_e32 v113, v5
	v_lshl_add_u64 v[112:113], v[100:101], 0, v[112:113]
	global_load_dword v193, v[112:113], off
	v_lshlrev_b32_e32 v113, 2, v114
	global_load_dword v194, v113, s[6:7]
	v_lshlrev_b32_e32 v112, 8, v116
	v_mov_b32_e32 v113, v5
	v_lshl_add_u64 v[100:101], v[100:101], 0, v[112:113]
	global_load_dword v195, v[100:101], off
	v_lshlrev_b32_e32 v101, 2, v116
	global_load_dword v196, v101, s[6:7]
	s_waitcnt vmcnt(0)
	v_add_u32_e32 v115, v19, v37
	s_lshl_b32 s10, s1, 1
	v_mul_f32_e32 v114, v125, v128
	v_mul_f32_e32 v112, v130, v131
	ds_write2_b32 v115, v114, v112 offset1:66
	v_mul_f32_e32 v114, v132, v133
	v_mul_f32_e32 v112, v134, v135
	ds_write2_b32 v115, v114, v112 offset0:132 offset1:198
	v_mul_f32_e32 v114, v136, v137
	v_mul_f32_e32 v112, v138, v139
	v_add_u32_e32 v113, 0x400, v115
	ds_write2_b32 v113, v114, v112 offset0:8 offset1:74
	v_add_u32_e32 v115, v19, v51
	v_mul_f32_e32 v114, v140, v141
	v_mul_f32_e32 v112, v142, v143
	ds_write2_b32 v115, v114, v112 offset1:66
	v_mul_f32_e32 v114, v144, v145
	v_mul_f32_e32 v112, v146, v148
	ds_write2_b32 v115, v114, v112 offset0:132 offset1:198
	v_mul_f32_e32 v114, v150, v151
	v_mul_f32_e32 v112, v152, v153
	v_add_u32_e32 v113, 0x400, v115
	ds_write2_b32 v113, v114, v112 offset0:8 offset1:74
	v_add_u32_e32 v115, v19, v65
	v_mul_f32_e32 v114, v154, v155
	v_mul_f32_e32 v112, v156, v157
	ds_write2_b32 v115, v114, v112 offset1:66
	v_mul_f32_e32 v114, v158, v159
	v_mul_f32_e32 v112, v160, v161
	ds_write2_b32 v115, v114, v112 offset0:132 offset1:198
	v_mul_f32_e32 v114, v162, v163
	v_mul_f32_e32 v112, v164, v165
	v_add_u32_e32 v113, 0x400, v115
	ds_write2_b32 v113, v114, v112 offset0:8 offset1:74
	v_add_u32_e32 v115, v19, v75
	v_mul_f32_e32 v114, v166, v168
	v_mul_f32_e32 v112, v170, v171
	ds_write2_b32 v115, v114, v112 offset1:66
	v_mul_f32_e32 v114, v172, v173
	v_mul_f32_e32 v112, v174, v176
	ds_write2_b32 v115, v114, v112 offset0:132 offset1:198
	v_mul_f32_e32 v114, v177, v178
	v_mul_f32_e32 v112, v179, v180
	v_add_u32_e32 v113, 0x400, v115
	ds_write2_b32 v113, v114, v112 offset0:8 offset1:74
	v_add_u32_e32 v115, v19, v77
	v_mul_f32_e32 v114, v181, v182
	v_mul_f32_e32 v112, v183, v184
	ds_write2_b32 v115, v114, v112 offset1:66
	v_mul_f32_e32 v114, v185, v186
	v_mul_f32_e32 v112, v187, v188
	ds_write2_b32 v115, v114, v112 offset0:132 offset1:198
	v_add_u32_e32 v115, 0x400, v115
	v_mul_f32_e32 v114, v189, v190
	v_mul_f32_e32 v112, v191, v192
	ds_write2_b32 v115, v114, v112 offset0:8 offset1:74
	v_mul_f32_e32 v114, v193, v194
	v_mul_f32_e32 v100, v195, v196
	ds_write2_b32 v115, v114, v100 offset0:140 offset1:206
	s_waitcnt lgkmcnt(0)
	ds_read2_b32 v[112:113], v81 offset1:33
	s_waitcnt lgkmcnt(0)
	v_cvt_pk_bf16_f32 v112, v112, v113
	ds_read2_b32 v[114:115], v81 offset0:66 offset1:99
	s_waitcnt lgkmcnt(0)
	v_cvt_pk_bf16_f32 v113, v114, v115
	ds_read2_b32 v[114:115], v81 offset0:132 offset1:165
	s_waitcnt lgkmcnt(0)
	v_cvt_pk_bf16_f32 v114, v114, v115
	ds_read2_b32 v[116:117], v81 offset0:198 offset1:231
	s_waitcnt lgkmcnt(0)
	v_cvt_pk_bf16_f32 v115, v116, v117
	v_or_b32_e32 v116, s0, v79
	v_lshl_add_u64 v[100:101], v[32:33], 0, s[10:11]
	v_lshlrev_b32_e32 v116, 11, v116
	v_mov_b32_e32 v117, v5
	v_lshl_add_u64 v[116:117], v[100:101], 0, v[116:117]
	v_add_co_u32_e32 v116, vcc, s23, v116
	s_nop 1
	v_addc_co_u32_e32 v117, vcc, 0, v117, vcc
	global_store_dwordx4 v[116:117], v[112:115], off
	ds_read2_b32 v[112:113], v81 offset0:8 offset1:41
	s_waitcnt lgkmcnt(0)
	v_cvt_pk_bf16_f32 v112, v112, v113
	ds_read2_b32 v[114:115], v81 offset0:74 offset1:107
	s_waitcnt lgkmcnt(0)
	v_cvt_pk_bf16_f32 v113, v114, v115
	ds_read2_b32 v[114:115], v81 offset0:140 offset1:173
	s_waitcnt lgkmcnt(0)
	v_cvt_pk_bf16_f32 v114, v114, v115
	ds_read2_b32 v[116:117], v81 offset0:206 offset1:239
	s_waitcnt lgkmcnt(0)
	v_cvt_pk_bf16_f32 v115, v116, v117
	v_or_b32_e32 v116, s0, v108
	v_lshlrev_b32_e32 v116, 11, v116
	v_mov_b32_e32 v117, v5
	v_lshl_add_u64 v[116:117], v[100:101], 0, v[116:117]
	v_add_co_u32_e32 v116, vcc, s23, v116
	s_nop 1
	v_addc_co_u32_e32 v117, vcc, 0, v117, vcc
	global_store_dwordx4 v[116:117], v[112:115], off
	ds_read2_b32 v[112:113], v81 offset0:16 offset1:49
	s_waitcnt lgkmcnt(0)
	v_cvt_pk_bf16_f32 v112, v112, v113
	ds_read2_b32 v[114:115], v81 offset0:82 offset1:115
	s_waitcnt lgkmcnt(0)
	v_cvt_pk_bf16_f32 v113, v114, v115
	ds_read2_b32 v[114:115], v81 offset0:148 offset1:181
	s_waitcnt lgkmcnt(0)
	v_cvt_pk_bf16_f32 v114, v114, v115
	ds_read2_b32 v[116:117], v81 offset0:214 offset1:247
	s_waitcnt lgkmcnt(0)
	v_cvt_pk_bf16_f32 v115, v116, v117
	v_or_b32_e32 v116, s0, v109
	v_lshlrev_b32_e32 v116, 11, v116
	v_mov_b32_e32 v117, v5
	v_lshl_add_u64 v[116:117], v[100:101], 0, v[116:117]
	v_add_co_u32_e32 v116, vcc, s23, v116
	s_nop 1
	v_addc_co_u32_e32 v117, vcc, 0, v117, vcc
	global_store_dwordx4 v[116:117], v[112:115], off
	ds_read2_b32 v[112:113], v81 offset0:24 offset1:57
	s_waitcnt lgkmcnt(0)
	v_cvt_pk_bf16_f32 v112, v112, v113
	ds_read2_b32 v[114:115], v81 offset0:90 offset1:123
	s_waitcnt lgkmcnt(0)
	v_cvt_pk_bf16_f32 v113, v114, v115
	ds_read2_b32 v[114:115], v81 offset0:156 offset1:189
	s_waitcnt lgkmcnt(0)
	v_cvt_pk_bf16_f32 v114, v114, v115
	ds_read2_b32 v[116:117], v81 offset0:222 offset1:255
	s_waitcnt lgkmcnt(0)
	v_cvt_pk_bf16_f32 v115, v116, v117
	v_or_b32_e32 v116, s0, v110
	v_lshlrev_b32_e32 v116, 11, v116
	v_mov_b32_e32 v117, v5
	v_lshl_add_u64 v[100:101], v[100:101], 0, v[116:117]
	v_add_co_u32_e32 v100, vcc, 0x60000, v100
	s_nop 1
	v_addc_co_u32_e32 v101, vcc, 0, v101, vcc
	global_store_dwordx4 v[100:101], v[112:115], off
	s_waitcnt lgkmcnt(0)

.LBB0_35:
	s_andn2_b64 vcc, exec, s[0:1]
	s_cbranch_vccnz .LBB0_37
	s_add_i32 s0, s21, 0x1800
	s_and_b32 s1, s0, 0x1fc0
	s_and_b32 s0, s21, 32
	s_lshl_b32 s10, s0, 2
	v_or_b32_e32 v114, s1, v3
	v_lshl_add_u64 v[100:101], v[28:29], 0, s[10:11]
	v_lshlrev_b32_e32 v112, 8, v114
	v_mov_b32_e32 v113, v5
	v_lshl_add_u64 v[112:113], v[100:101], 0, v[112:113]
	global_load_dword v125, v[112:113], off
	v_lshlrev_b32_e32 v113, 2, v114
	global_load_dword v128, v113, s[6:7]
	v_or_b32_e32 v116, s1, v39
	v_lshlrev_b32_e32 v112, 8, v116
	v_mov_b32_e32 v113, v5
	v_lshl_add_u64 v[112:113], v[100:101], 0, v[112:113]
	global_load_dword v130, v[112:113], off
	v_lshlrev_b32_e32 v113, 2, v116
	global_load_dword v131, v113, s[6:7]
	v_or_b32_e32 v116, s1, v43
	v_or_b32_e32 v114, s1, v41
	v_lshlrev_b32_e32 v112, 8, v114
	v_mov_b32_e32 v113, v5
	v_lshl_add_u64 v[112:113], v[100:101], 0, v[112:113]
	global_load_dword v132, v[112:113], off
	v_lshlrev_b32_e32 v113, 2, v114
	global_load_dword v133, v113, s[6:7]
	v_lshlrev_b32_e32 v112, 8, v116
	v_mov_b32_e32 v113, v5
	v_lshl_add_u64 v[112:113], v[100:101], 0, v[112:113]
	global_load_dword v134, v[112:113], off
	v_lshlrev_b32_e32 v113, 2, v116
	global_load_dword v135, v113, s[6:7]
	v_or_b32_e32 v116, s1, v47
	v_or_b32_e32 v114, s1, v45
	v_lshlrev_b32_e32 v112, 8, v114
	v_mov_b32_e32 v113, v5
	v_lshl_add_u64 v[112:113], v[100:101], 0, v[112:113]
	global_load_dword v136, v[112:113], off
	v_lshlrev_b32_e32 v113, 2, v114
	global_load_dword v137, v113, s[6:7]
	v_lshlrev_b32_e32 v112, 8, v116
	v_mov_b32_e32 v113, v5
	v_lshl_add_u64 v[112:113], v[100:101], 0, v[112:113]
	global_load_dword v138, v[112:113], off
	v_lshlrev_b32_e32 v113, 2, v116
	global_load_dword v139, v113, s[6:7]
	v_or_b32_e32 v116, s1, v53
	v_or_b32_e32 v114, s1, v49
	v_lshlrev_b32_e32 v112, 8, v114
	v_mov_b32_e32 v113, v5
	v_lshl_add_u64 v[112:113], v[100:101], 0, v[112:113]
	global_load_dword v140, v[112:113], off
	v_lshlrev_b32_e32 v113, 2, v114
	global_load_dword v141, v113, s[6:7]
	v_lshlrev_b32_e32 v112, 8, v116
	v_mov_b32_e32 v113, v5
	v_lshl_add_u64 v[112:113], v[100:101], 0, v[112:113]
	global_load_dword v142, v[112:113], off
	v_lshlrev_b32_e32 v113, 2, v116
	global_load_dword v143, v113, s[6:7]
	v_or_b32_e32 v116, s1, v57
	v_or_b32_e32 v114, s1, v55
	v_lshlrev_b32_e32 v112, 8, v114
	v_mov_b32_e32 v113, v5
	v_lshl_add_u64 v[112:113], v[100:101], 0, v[112:113]
	global_load_dword v144, v[112:113], off
	v_lshlrev_b32_e32 v113, 2, v114
	global_load_dword v145, v113, s[6:7]
	v_lshlrev_b32_e32 v112, 8, v116
	v_mov_b32_e32 v113, v5
	v_lshl_add_u64 v[112:113], v[100:101], 0, v[112:113]
	global_load_dword v146, v[112:113], off
	v_lshlrev_b32_e32 v113, 2, v116
	global_load_dword v148, v113, s[6:7]
	v_or_b32_e32 v116, s1, v61
	v_or_b32_e32 v114, s1, v59
	v_lshlrev_b32_e32 v112, 8, v114
	v_mov_b32_e32 v113, v5
	v_lshl_add_u64 v[112:113], v[100:101], 0, v[112:113]
	global_load_dword v150, v[112:113], off
	v_lshlrev_b32_e32 v113, 2, v114
	global_load_dword v151, v113, s[6:7]
	v_lshlrev_b32_e32 v112, 8, v116
	v_mov_b32_e32 v113, v5
	v_lshl_add_u64 v[112:113], v[100:101], 0, v[112:113]
	global_load_dword v152, v[112:113], off
	v_lshlrev_b32_e32 v113, 2, v116
	global_load_dword v153, v113, s[6:7]
	v_or_b32_e32 v116, s1, v67
	v_or_b32_e32 v114, s1, v63
	v_lshlrev_b32_e32 v112, 8, v114
	v_mov_b32_e32 v113, v5
	v_lshl_add_u64 v[112:113], v[100:101], 0, v[112:113]
	global_load_dword v154, v[112:113], off
	v_lshlrev_b32_e32 v113, 2, v114
	global_load_dword v155, v113, s[6:7]
	v_lshlrev_b32_e32 v112, 8, v116
	v_mov_b32_e32 v113, v5
	v_lshl_add_u64 v[112:113], v[100:101], 0, v[112:113]
	global_load_dword v156, v[112:113], off
	v_lshlrev_b32_e32 v113, 2, v116
	global_load_dword v157, v113, s[6:7]
	v_or_b32_e32 v116, s1, v71
	v_or_b32_e32 v114, s1, v69
	v_lshlrev_b32_e32 v112, 8, v114
	v_mov_b32_e32 v113, v5
	v_lshl_add_u64 v[112:113], v[100:101], 0, v[112:113]
	global_load_dword v158, v[112:113], off
	v_lshlrev_b32_e32 v113, 2, v114
	global_load_dword v159, v113, s[6:7]
	v_lshlrev_b32_e32 v112, 8, v116
	v_mov_b32_e32 v113, v5
	v_lshl_add_u64 v[112:113], v[100:101], 0, v[112:113]
	global_load_dword v160, v[112:113], off
	v_lshlrev_b32_e32 v113, 2, v116
	global_load_dword v161, v113, s[6:7]
	v_or_b32_e32 v116, s1, v83
	v_or_b32_e32 v114, s1, v73
	v_lshlrev_b32_e32 v112, 8, v114
	v_mov_b32_e32 v113, v5
	v_lshl_add_u64 v[112:113], v[100:101], 0, v[112:113]
	global_load_dword v162, v[112:113], off
	v_lshlrev_b32_e32 v113, 2, v114
	global_load_dword v163, v113, s[6:7]
	v_lshlrev_b32_e32 v112, 8, v116
	v_mov_b32_e32 v113, v5
	v_lshl_add_u64 v[112:113], v[100:101], 0, v[112:113]
	global_load_dword v164, v[112:113], off
	v_lshlrev_b32_e32 v113, 2, v116
	global_load_dword v165, v113, s[6:7]
	v_or_b32_e32 v116, s1, v87
	v_or_b32_e32 v114, s1, v85
	v_lshlrev_b32_e32 v112, 8, v114
	v_mov_b32_e32 v113, v5
	v_lshl_add_u64 v[112:113], v[100:101], 0, v[112:113]
	global_load_dword v166, v[112:113], off
	v_lshlrev_b32_e32 v113, 2, v114
	global_load_dword v168, v113, s[6:7]
	v_lshlrev_b32_e32 v112, 8, v116
	v_mov_b32_e32 v113, v5
	v_lshl_add_u64 v[112:113], v[100:101], 0, v[112:113]
	global_load_dword v170, v[112:113], off
	v_lshlrev_b32_e32 v113, 2, v116
	global_load_dword v171, v113, s[6:7]
	v_or_b32_e32 v116, s1, v91
	v_or_b32_e32 v114, s1, v89
	v_lshlrev_b32_e32 v112, 8, v114
	v_mov_b32_e32 v113, v5
	v_lshl_add_u64 v[112:113], v[100:101], 0, v[112:113]
	global_load_dword v172, v[112:113], off
	v_lshlrev_b32_e32 v113, 2, v114
	global_load_dword v173, v113, s[6:7]
	v_lshlrev_b32_e32 v112, 8, v116
	v_mov_b32_e32 v113, v5
	v_lshl_add_u64 v[112:113], v[100:101], 0, v[112:113]
	global_load_dword v174, v[112:113], off
	v_lshlrev_b32_e32 v113, 2, v116
	global_load_dword v176, v113, s[6:7]
	v_or_b32_e32 v116, s1, v95
	v_or_b32_e32 v114, s1, v93
	v_lshlrev_b32_e32 v112, 8, v114
	v_mov_b32_e32 v113, v5
	v_lshl_add_u64 v[112:113], v[100:101], 0, v[112:113]
	global_load_dword v177, v[112:113], off
	v_lshlrev_b32_e32 v113, 2, v114
	global_load_dword v178, v113, s[6:7]
	v_lshlrev_b32_e32 v112, 8, v116
	v_mov_b32_e32 v113, v5
	v_lshl_add_u64 v[112:113], v[100:101], 0, v[112:113]
	global_load_dword v179, v[112:113], off
	v_lshlrev_b32_e32 v113, 2, v116
	global_load_dword v180, v113, s[6:7]
	v_or_b32_e32 v116, s1, v99
	v_or_b32_e32 v114, s1, v97
	v_lshlrev_b32_e32 v112, 8, v114
	v_mov_b32_e32 v113, v5
	v_lshl_add_u64 v[112:113], v[100:101], 0, v[112:113]
	s_waitcnt vmcnt(16)
	global_load_dword v181, v[112:113], off
	v_lshlrev_b32_e32 v113, 2, v114
	global_load_dword v182, v113, s[6:7]
	v_lshlrev_b32_e32 v112, 8, v116
	v_mov_b32_e32 v113, v5
	v_lshl_add_u64 v[112:113], v[100:101], 0, v[112:113]
	global_load_dword v183, v[112:113], off
	v_lshlrev_b32_e32 v113, 2, v116
	global_load_dword v184, v113, s[6:7]
	v_or_b32_e32 v116, s1, v103
	v_or_b32_e32 v114, s1, v102
	v_lshlrev_b32_e32 v112, 8, v114
	v_mov_b32_e32 v113, v5
	v_lshl_add_u64 v[112:113], v[100:101], 0, v[112:113]
	global_load_dword v185, v[112:113], off
	v_lshlrev_b32_e32 v113, 2, v114
	global_load_dword v186, v113, s[6:7]
	v_lshlrev_b32_e32 v112, 8, v116
	v_mov_b32_e32 v113, v5
	v_lshl_add_u64 v[112:113], v[100:101], 0, v[112:113]
	global_load_dword v187, v[112:113], off
	v_lshlrev_b32_e32 v113, 2, v116
	global_load_dword v188, v113, s[6:7]
	v_or_b32_e32 v116, s1, v105
	v_or_b32_e32 v114, s1, v104
	v_lshlrev_b32_e32 v112, 8, v114
	v_mov_b32_e32 v113, v5
	v_lshl_add_u64 v[112:113], v[100:101], 0, v[112:113]
	global_load_dword v189, v[112:113], off
	v_lshlrev_b32_e32 v113, 2, v114
	global_load_dword v190, v113, s[6:7]
	v_lshlrev_b32_e32 v112, 8, v116
	v_mov_b32_e32 v113, v5
	v_lshl_add_u64 v[112:113], v[100:101], 0, v[112:113]
	global_load_dword v191, v[112:113], off
	v_lshlrev_b32_e32 v113, 2, v116
	global_load_dword v192, v113, s[6:7]
	v_or_b32_e32 v116, s1, v107
	v_or_b32_e32 v114, s1, v106
	v_lshlrev_b32_e32 v112, 8, v114
	v_mov_b32_e32 v113, v5
	v_lshl_add_u64 v[112:113], v[100:101], 0, v[112:113]
	global_load_dword v193, v[112:113], off
	v_lshlrev_b32_e32 v113, 2, v114
	global_load_dword v194, v113, s[6:7]
	v_lshlrev_b32_e32 v112, 8, v116
	v_mov_b32_e32 v113, v5
	v_lshl_add_u64 v[100:101], v[100:101], 0, v[112:113]
	global_load_dword v195, v[100:101], off
	v_lshlrev_b32_e32 v101, 2, v116
	global_load_dword v196, v101, s[6:7]
	s_waitcnt vmcnt(0)
	v_add_u32_e32 v115, v19, v37
	s_lshl_b32 s10, s1, 1
	v_sub_f32_e32 v113, 1.0, v128
	v_mul_f32_e32 v114, v125, v113
	v_sub_f32_e32 v113, 1.0, v131
	v_mul_f32_e32 v112, v130, v113
	ds_write2_b32 v115, v114, v112 offset1:66
	v_sub_f32_e32 v113, 1.0, v133
	v_mul_f32_e32 v114, v132, v113
	v_sub_f32_e32 v113, 1.0, v135
	v_mul_f32_e32 v112, v134, v113
	ds_write2_b32 v115, v114, v112 offset0:132 offset1:198
	v_sub_f32_e32 v113, 1.0, v137
	v_mul_f32_e32 v114, v136, v113
	v_sub_f32_e32 v113, 1.0, v139
	v_mul_f32_e32 v112, v138, v113
	v_add_u32_e32 v113, 0x400, v115
	ds_write2_b32 v113, v114, v112 offset0:8 offset1:74
	v_add_u32_e32 v115, v19, v51
	v_sub_f32_e32 v113, 1.0, v141
	v_mul_f32_e32 v114, v140, v113
	v_sub_f32_e32 v113, 1.0, v143
	v_mul_f32_e32 v112, v142, v113
	ds_write2_b32 v115, v114, v112 offset1:66
	v_sub_f32_e32 v113, 1.0, v145
	v_mul_f32_e32 v114, v144, v113
	v_sub_f32_e32 v113, 1.0, v148
	v_mul_f32_e32 v112, v146, v113
	ds_write2_b32 v115, v114, v112 offset0:132 offset1:198
	v_sub_f32_e32 v113, 1.0, v151
	v_mul_f32_e32 v114, v150, v113
	v_sub_f32_e32 v113, 1.0, v153
	v_mul_f32_e32 v112, v152, v113
	v_add_u32_e32 v113, 0x400, v115
	ds_write2_b32 v113, v114, v112 offset0:8 offset1:74
	v_add_u32_e32 v115, v19, v65
	v_sub_f32_e32 v113, 1.0, v155
	v_mul_f32_e32 v114, v154, v113
	v_sub_f32_e32 v113, 1.0, v157
	v_mul_f32_e32 v112, v156, v113
	ds_write2_b32 v115, v114, v112 offset1:66
	v_sub_f32_e32 v113, 1.0, v159
	v_mul_f32_e32 v114, v158, v113
	v_sub_f32_e32 v113, 1.0, v161
	v_mul_f32_e32 v112, v160, v113
	ds_write2_b32 v115, v114, v112 offset0:132 offset1:198
	v_sub_f32_e32 v113, 1.0, v163
	v_mul_f32_e32 v114, v162, v113
	v_sub_f32_e32 v113, 1.0, v165
	v_mul_f32_e32 v112, v164, v113
	v_add_u32_e32 v113, 0x400, v115
	ds_write2_b32 v113, v114, v112 offset0:8 offset1:74
	v_add_u32_e32 v115, v19, v75
	v_sub_f32_e32 v113, 1.0, v168
	v_mul_f32_e32 v114, v166, v113
	v_sub_f32_e32 v113, 1.0, v171
	v_mul_f32_e32 v112, v170, v113
	ds_write2_b32 v115, v114, v112 offset1:66
	v_sub_f32_e32 v113, 1.0, v173
	v_mul_f32_e32 v114, v172, v113
	v_sub_f32_e32 v113, 1.0, v176
	v_mul_f32_e32 v112, v174, v113
	ds_write2_b32 v115, v114, v112 offset0:132 offset1:198
	v_sub_f32_e32 v113, 1.0, v178
	v_mul_f32_e32 v114, v177, v113
	v_sub_f32_e32 v113, 1.0, v180
	v_mul_f32_e32 v112, v179, v113
	v_add_u32_e32 v113, 0x400, v115
	ds_write2_b32 v113, v114, v112 offset0:8 offset1:74
	v_add_u32_e32 v115, v19, v77
	v_sub_f32_e32 v113, 1.0, v182
	v_mul_f32_e32 v114, v181, v113
	v_sub_f32_e32 v113, 1.0, v184
	v_mul_f32_e32 v112, v183, v113
	ds_write2_b32 v115, v114, v112 offset1:66
	v_sub_f32_e32 v113, 1.0, v186
	v_mul_f32_e32 v114, v185, v113
	v_sub_f32_e32 v113, 1.0, v188
	v_mul_f32_e32 v112, v187, v113
	ds_write2_b32 v115, v114, v112 offset0:132 offset1:198
	v_add_u32_e32 v115, 0x400, v115
	v_sub_f32_e32 v113, 1.0, v190
	v_mul_f32_e32 v114, v189, v113
	v_sub_f32_e32 v113, 1.0, v192
	v_mul_f32_e32 v112, v191, v113
	ds_write2_b32 v115, v114, v112 offset0:8 offset1:74
	v_sub_f32_e32 v113, 1.0, v194
	v_mul_f32_e32 v114, v193, v113
	v_sub_f32_e32 v101, 1.0, v196
	v_mul_f32_e32 v100, v195, v101
	ds_write2_b32 v115, v114, v100 offset0:140 offset1:206
	s_waitcnt lgkmcnt(0)
	ds_read2_b32 v[112:113], v81 offset1:33
	s_waitcnt lgkmcnt(0)
	v_cvt_pk_bf16_f32 v112, v112, v113
	ds_read2_b32 v[114:115], v81 offset0:66 offset1:99
	s_waitcnt lgkmcnt(0)
	v_cvt_pk_bf16_f32 v113, v114, v115
	ds_read2_b32 v[114:115], v81 offset0:132 offset1:165
	s_waitcnt lgkmcnt(0)
	v_cvt_pk_bf16_f32 v114, v114, v115
	ds_read2_b32 v[116:117], v81 offset0:198 offset1:231
	s_waitcnt lgkmcnt(0)
	v_cvt_pk_bf16_f32 v115, v116, v117
	v_or_b32_e32 v116, s0, v79
	v_lshl_add_u64 v[100:101], v[32:33], 0, s[10:11]
	v_lshlrev_b32_e32 v116, 11, v116
	v_mov_b32_e32 v117, v5
	v_lshl_add_u64 v[116:117], v[100:101], 0, v[116:117]
	v_add_co_u32_e32 v116, vcc, s24, v116
	s_nop 1
	v_addc_co_u32_e32 v117, vcc, 0, v117, vcc
	global_store_dwordx4 v[116:117], v[112:115], off
	ds_read2_b32 v[112:113], v81 offset0:8 offset1:41
	s_waitcnt lgkmcnt(0)
	v_cvt_pk_bf16_f32 v112, v112, v113
	ds_read2_b32 v[114:115], v81 offset0:74 offset1:107
	s_waitcnt lgkmcnt(0)
	v_cvt_pk_bf16_f32 v113, v114, v115
	ds_read2_b32 v[114:115], v81 offset0:140 offset1:173
	s_waitcnt lgkmcnt(0)
	v_cvt_pk_bf16_f32 v114, v114, v115
	ds_read2_b32 v[116:117], v81 offset0:206 offset1:239
	s_waitcnt lgkmcnt(0)
	v_cvt_pk_bf16_f32 v115, v116, v117
	v_or_b32_e32 v116, s0, v108
	v_lshlrev_b32_e32 v116, 11, v116
	v_mov_b32_e32 v117, v5
	v_lshl_add_u64 v[116:117], v[100:101], 0, v[116:117]
	v_add_co_u32_e32 v116, vcc, s24, v116
	s_nop 1
	v_addc_co_u32_e32 v117, vcc, 0, v117, vcc
	global_store_dwordx4 v[116:117], v[112:115], off
	ds_read2_b32 v[112:113], v81 offset0:16 offset1:49
	s_waitcnt lgkmcnt(0)
	v_cvt_pk_bf16_f32 v112, v112, v113
	ds_read2_b32 v[114:115], v81 offset0:82 offset1:115
	s_waitcnt lgkmcnt(0)
	v_cvt_pk_bf16_f32 v113, v114, v115
	ds_read2_b32 v[114:115], v81 offset0:148 offset1:181
	s_waitcnt lgkmcnt(0)
	v_cvt_pk_bf16_f32 v114, v114, v115
	ds_read2_b32 v[116:117], v81 offset0:214 offset1:247
	s_waitcnt lgkmcnt(0)
	v_cvt_pk_bf16_f32 v115, v116, v117
	v_or_b32_e32 v116, s0, v109
	v_lshlrev_b32_e32 v116, 11, v116
	v_mov_b32_e32 v117, v5
	v_lshl_add_u64 v[116:117], v[100:101], 0, v[116:117]
	v_add_co_u32_e32 v116, vcc, s24, v116
	s_nop 1
	v_addc_co_u32_e32 v117, vcc, 0, v117, vcc
	global_store_dwordx4 v[116:117], v[112:115], off
	ds_read2_b32 v[112:113], v81 offset0:24 offset1:57
	s_waitcnt lgkmcnt(0)
	v_cvt_pk_bf16_f32 v112, v112, v113
	ds_read2_b32 v[114:115], v81 offset0:90 offset1:123
	s_waitcnt lgkmcnt(0)
	v_cvt_pk_bf16_f32 v113, v114, v115
	ds_read2_b32 v[114:115], v81 offset0:156 offset1:189
	s_waitcnt lgkmcnt(0)
	v_cvt_pk_bf16_f32 v114, v114, v115
	ds_read2_b32 v[116:117], v81 offset0:222 offset1:255
	s_waitcnt lgkmcnt(0)
	v_cvt_pk_bf16_f32 v115, v116, v117
	v_or_b32_e32 v116, s0, v110
	v_lshlrev_b32_e32 v116, 11, v116
	v_mov_b32_e32 v117, v5
	v_lshl_add_u64 v[100:101], v[100:101], 0, v[116:117]
	v_add_co_u32_e32 v100, vcc, 0x40000, v100
	s_nop 1
	v_addc_co_u32_e32 v101, vcc, 0, v101, vcc
	global_store_dwordx4 v[100:101], v[112:115], off
	s_waitcnt lgkmcnt(0)

.LBB0_38:
	s_andn2_b64 vcc, exec, s[0:1]
	s_cbranch_vccnz .LBB0_40
	s_add_i32 s0, s21, 0x1c00
	s_and_b32 s1, s0, 0x1fc0
	s_and_b32 s0, s21, 32
	s_lshl_b32 s10, s0, 2
	v_or_b32_e32 v114, s1, v3
	v_lshl_add_u64 v[100:101], v[30:31], 0, s[10:11]
	v_lshlrev_b32_e32 v112, 8, v114
	v_mov_b32_e32 v113, v5
	v_lshl_add_u64 v[112:113], v[100:101], 0, v[112:113]
	global_load_dword v125, v[112:113], off
	v_lshlrev_b32_e32 v113, 2, v114
	global_load_dword v128, v113, s[8:9]
	v_or_b32_e32 v116, s1, v39
	v_lshlrev_b32_e32 v112, 8, v116
	v_mov_b32_e32 v113, v5
	v_lshl_add_u64 v[112:113], v[100:101], 0, v[112:113]
	global_load_dword v130, v[112:113], off
	v_lshlrev_b32_e32 v113, 2, v116
	global_load_dword v131, v113, s[8:9]
	v_or_b32_e32 v116, s1, v43
	v_or_b32_e32 v114, s1, v41
	v_lshlrev_b32_e32 v112, 8, v114
	v_mov_b32_e32 v113, v5
	v_lshl_add_u64 v[112:113], v[100:101], 0, v[112:113]
	global_load_dword v132, v[112:113], off
	v_lshlrev_b32_e32 v113, 2, v114
	global_load_dword v133, v113, s[8:9]
	v_lshlrev_b32_e32 v112, 8, v116
	v_mov_b32_e32 v113, v5
	v_lshl_add_u64 v[112:113], v[100:101], 0, v[112:113]
	global_load_dword v134, v[112:113], off
	v_lshlrev_b32_e32 v113, 2, v116
	global_load_dword v135, v113, s[8:9]
	v_or_b32_e32 v116, s1, v47
	v_or_b32_e32 v114, s1, v45
	v_lshlrev_b32_e32 v112, 8, v114
	v_mov_b32_e32 v113, v5
	v_lshl_add_u64 v[112:113], v[100:101], 0, v[112:113]
	global_load_dword v136, v[112:113], off
	v_lshlrev_b32_e32 v113, 2, v114
	global_load_dword v137, v113, s[8:9]
	v_lshlrev_b32_e32 v112, 8, v116
	v_mov_b32_e32 v113, v5
	v_lshl_add_u64 v[112:113], v[100:101], 0, v[112:113]
	global_load_dword v138, v[112:113], off
	v_lshlrev_b32_e32 v113, 2, v116
	global_load_dword v139, v113, s[8:9]
	v_or_b32_e32 v116, s1, v53
	v_or_b32_e32 v114, s1, v49
	v_lshlrev_b32_e32 v112, 8, v114
	v_mov_b32_e32 v113, v5
	v_lshl_add_u64 v[112:113], v[100:101], 0, v[112:113]
	global_load_dword v140, v[112:113], off
	v_lshlrev_b32_e32 v113, 2, v114
	global_load_dword v141, v113, s[8:9]
	v_lshlrev_b32_e32 v112, 8, v116
	v_mov_b32_e32 v113, v5
	v_lshl_add_u64 v[112:113], v[100:101], 0, v[112:113]
	global_load_dword v142, v[112:113], off
	v_lshlrev_b32_e32 v113, 2, v116
	global_load_dword v143, v113, s[8:9]
	v_or_b32_e32 v116, s1, v57
	v_or_b32_e32 v114, s1, v55
	v_lshlrev_b32_e32 v112, 8, v114
	v_mov_b32_e32 v113, v5
	v_lshl_add_u64 v[112:113], v[100:101], 0, v[112:113]
	global_load_dword v144, v[112:113], off
	v_lshlrev_b32_e32 v113, 2, v114
	global_load_dword v145, v113, s[8:9]
	v_lshlrev_b32_e32 v112, 8, v116
	v_mov_b32_e32 v113, v5
	v_lshl_add_u64 v[112:113], v[100:101], 0, v[112:113]
	global_load_dword v146, v[112:113], off
	v_lshlrev_b32_e32 v113, 2, v116
	global_load_dword v148, v113, s[8:9]
	v_or_b32_e32 v116, s1, v61
	v_or_b32_e32 v114, s1, v59
	v_lshlrev_b32_e32 v112, 8, v114
	v_mov_b32_e32 v113, v5
	v_lshl_add_u64 v[112:113], v[100:101], 0, v[112:113]
	global_load_dword v150, v[112:113], off
	v_lshlrev_b32_e32 v113, 2, v114
	global_load_dword v151, v113, s[8:9]
	v_lshlrev_b32_e32 v112, 8, v116
	v_mov_b32_e32 v113, v5
	v_lshl_add_u64 v[112:113], v[100:101], 0, v[112:113]
	global_load_dword v152, v[112:113], off
	v_lshlrev_b32_e32 v113, 2, v116
	global_load_dword v153, v113, s[8:9]
	v_or_b32_e32 v116, s1, v67
	v_or_b32_e32 v114, s1, v63
	v_lshlrev_b32_e32 v112, 8, v114
	v_mov_b32_e32 v113, v5
	v_lshl_add_u64 v[112:113], v[100:101], 0, v[112:113]
	global_load_dword v154, v[112:113], off
	v_lshlrev_b32_e32 v113, 2, v114
	global_load_dword v155, v113, s[8:9]
	v_lshlrev_b32_e32 v112, 8, v116
	v_mov_b32_e32 v113, v5
	v_lshl_add_u64 v[112:113], v[100:101], 0, v[112:113]
	global_load_dword v156, v[112:113], off
	v_lshlrev_b32_e32 v113, 2, v116
	global_load_dword v157, v113, s[8:9]
	v_or_b32_e32 v116, s1, v71
	v_or_b32_e32 v114, s1, v69
	v_lshlrev_b32_e32 v112, 8, v114
	v_mov_b32_e32 v113, v5
	v_lshl_add_u64 v[112:113], v[100:101], 0, v[112:113]
	global_load_dword v158, v[112:113], off
	v_lshlrev_b32_e32 v113, 2, v114
	global_load_dword v159, v113, s[8:9]
	v_lshlrev_b32_e32 v112, 8, v116
	v_mov_b32_e32 v113, v5
	v_lshl_add_u64 v[112:113], v[100:101], 0, v[112:113]
	global_load_dword v160, v[112:113], off
	v_lshlrev_b32_e32 v113, 2, v116
	global_load_dword v161, v113, s[8:9]
	v_or_b32_e32 v116, s1, v83
	v_or_b32_e32 v114, s1, v73
	v_lshlrev_b32_e32 v112, 8, v114
	v_mov_b32_e32 v113, v5
	v_lshl_add_u64 v[112:113], v[100:101], 0, v[112:113]
	global_load_dword v162, v[112:113], off
	v_lshlrev_b32_e32 v113, 2, v114
	global_load_dword v163, v113, s[8:9]
	v_lshlrev_b32_e32 v112, 8, v116
	v_mov_b32_e32 v113, v5
	v_lshl_add_u64 v[112:113], v[100:101], 0, v[112:113]
	global_load_dword v164, v[112:113], off
	v_lshlrev_b32_e32 v113, 2, v116
	global_load_dword v165, v113, s[8:9]
	v_or_b32_e32 v116, s1, v87
	v_or_b32_e32 v114, s1, v85
	v_lshlrev_b32_e32 v112, 8, v114
	v_mov_b32_e32 v113, v5
	v_lshl_add_u64 v[112:113], v[100:101], 0, v[112:113]
	global_load_dword v166, v[112:113], off
	v_lshlrev_b32_e32 v113, 2, v114
	global_load_dword v168, v113, s[8:9]
	v_lshlrev_b32_e32 v112, 8, v116
	v_mov_b32_e32 v113, v5
	v_lshl_add_u64 v[112:113], v[100:101], 0, v[112:113]
	global_load_dword v170, v[112:113], off
	v_lshlrev_b32_e32 v113, 2, v116
	global_load_dword v171, v113, s[8:9]
	v_or_b32_e32 v116, s1, v91
	v_or_b32_e32 v114, s1, v89
	v_lshlrev_b32_e32 v112, 8, v114
	v_mov_b32_e32 v113, v5
	v_lshl_add_u64 v[112:113], v[100:101], 0, v[112:113]
	global_load_dword v172, v[112:113], off
	v_lshlrev_b32_e32 v113, 2, v114
	global_load_dword v173, v113, s[8:9]
	v_lshlrev_b32_e32 v112, 8, v116
	v_mov_b32_e32 v113, v5
	v_lshl_add_u64 v[112:113], v[100:101], 0, v[112:113]
	global_load_dword v174, v[112:113], off
	v_lshlrev_b32_e32 v113, 2, v116
	global_load_dword v176, v113, s[8:9]
	v_or_b32_e32 v116, s1, v95
	v_or_b32_e32 v114, s1, v93
	v_lshlrev_b32_e32 v112, 8, v114
	v_mov_b32_e32 v113, v5
	v_lshl_add_u64 v[112:113], v[100:101], 0, v[112:113]
	global_load_dword v177, v[112:113], off
	v_lshlrev_b32_e32 v113, 2, v114
	global_load_dword v178, v113, s[8:9]
	v_lshlrev_b32_e32 v112, 8, v116
	v_mov_b32_e32 v113, v5
	v_lshl_add_u64 v[112:113], v[100:101], 0, v[112:113]
	global_load_dword v179, v[112:113], off
	v_lshlrev_b32_e32 v113, 2, v116
	global_load_dword v180, v113, s[8:9]
	v_or_b32_e32 v116, s1, v99
	v_or_b32_e32 v114, s1, v97
	v_lshlrev_b32_e32 v112, 8, v114
	v_mov_b32_e32 v113, v5
	v_lshl_add_u64 v[112:113], v[100:101], 0, v[112:113]
	s_waitcnt vmcnt(16)
	global_load_dword v181, v[112:113], off
	v_lshlrev_b32_e32 v113, 2, v114
	global_load_dword v182, v113, s[8:9]
	v_lshlrev_b32_e32 v112, 8, v116
	v_mov_b32_e32 v113, v5
	v_lshl_add_u64 v[112:113], v[100:101], 0, v[112:113]
	global_load_dword v183, v[112:113], off
	v_lshlrev_b32_e32 v113, 2, v116
	global_load_dword v184, v113, s[8:9]
	v_or_b32_e32 v116, s1, v103
	v_or_b32_e32 v114, s1, v102
	v_lshlrev_b32_e32 v112, 8, v114
	v_mov_b32_e32 v113, v5
	v_lshl_add_u64 v[112:113], v[100:101], 0, v[112:113]
	global_load_dword v185, v[112:113], off
	v_lshlrev_b32_e32 v113, 2, v114
	global_load_dword v186, v113, s[8:9]
	v_lshlrev_b32_e32 v112, 8, v116
	v_mov_b32_e32 v113, v5
	v_lshl_add_u64 v[112:113], v[100:101], 0, v[112:113]
	global_load_dword v187, v[112:113], off
	v_lshlrev_b32_e32 v113, 2, v116
	global_load_dword v188, v113, s[8:9]
	v_or_b32_e32 v116, s1, v105
	v_or_b32_e32 v114, s1, v104
	v_lshlrev_b32_e32 v112, 8, v114
	v_mov_b32_e32 v113, v5
	v_lshl_add_u64 v[112:113], v[100:101], 0, v[112:113]
	global_load_dword v189, v[112:113], off
	v_lshlrev_b32_e32 v113, 2, v114
	global_load_dword v190, v113, s[8:9]
	v_lshlrev_b32_e32 v112, 8, v116
	v_mov_b32_e32 v113, v5
	v_lshl_add_u64 v[112:113], v[100:101], 0, v[112:113]
	global_load_dword v191, v[112:113], off
	v_lshlrev_b32_e32 v113, 2, v116
	global_load_dword v192, v113, s[8:9]
	v_or_b32_e32 v116, s1, v107
	v_or_b32_e32 v114, s1, v106
	v_lshlrev_b32_e32 v112, 8, v114
	v_mov_b32_e32 v113, v5
	v_lshl_add_u64 v[112:113], v[100:101], 0, v[112:113]
	global_load_dword v193, v[112:113], off
	v_lshlrev_b32_e32 v113, 2, v114
	global_load_dword v194, v113, s[8:9]
	v_lshlrev_b32_e32 v112, 8, v116
	v_mov_b32_e32 v113, v5
	v_lshl_add_u64 v[100:101], v[100:101], 0, v[112:113]
	global_load_dword v195, v[100:101], off
	v_lshlrev_b32_e32 v101, 2, v116
	global_load_dword v196, v101, s[8:9]
	s_waitcnt vmcnt(0)
	v_add_u32_e32 v115, v19, v37
	s_lshl_b32 s10, s1, 1
	v_mul_f32_e32 v114, v125, v128
	v_mul_f32_e32 v112, v130, v131
	ds_write2_b32 v115, v114, v112 offset1:66
	v_mul_f32_e32 v114, v132, v133
	v_mul_f32_e32 v112, v134, v135
	ds_write2_b32 v115, v114, v112 offset0:132 offset1:198
	v_mul_f32_e32 v114, v136, v137
	v_mul_f32_e32 v112, v138, v139
	v_add_u32_e32 v113, 0x400, v115
	ds_write2_b32 v113, v114, v112 offset0:8 offset1:74
	v_add_u32_e32 v115, v19, v51
	v_mul_f32_e32 v114, v140, v141
	v_mul_f32_e32 v112, v142, v143
	ds_write2_b32 v115, v114, v112 offset1:66
	v_mul_f32_e32 v114, v144, v145
	v_mul_f32_e32 v112, v146, v148
	ds_write2_b32 v115, v114, v112 offset0:132 offset1:198
	v_mul_f32_e32 v114, v150, v151
	v_mul_f32_e32 v112, v152, v153
	v_add_u32_e32 v113, 0x400, v115
	ds_write2_b32 v113, v114, v112 offset0:8 offset1:74
	v_add_u32_e32 v115, v19, v65
	v_mul_f32_e32 v114, v154, v155
	v_mul_f32_e32 v112, v156, v157
	ds_write2_b32 v115, v114, v112 offset1:66
	v_mul_f32_e32 v114, v158, v159
	v_mul_f32_e32 v112, v160, v161
	ds_write2_b32 v115, v114, v112 offset0:132 offset1:198
	v_mul_f32_e32 v114, v162, v163
	v_mul_f32_e32 v112, v164, v165
	v_add_u32_e32 v113, 0x400, v115
	ds_write2_b32 v113, v114, v112 offset0:8 offset1:74
	v_add_u32_e32 v115, v19, v75
	v_mul_f32_e32 v114, v166, v168
	v_mul_f32_e32 v112, v170, v171
	ds_write2_b32 v115, v114, v112 offset1:66
	v_mul_f32_e32 v114, v172, v173
	v_mul_f32_e32 v112, v174, v176
	ds_write2_b32 v115, v114, v112 offset0:132 offset1:198
	v_mul_f32_e32 v114, v177, v178
	v_mul_f32_e32 v112, v179, v180
	v_add_u32_e32 v113, 0x400, v115
	ds_write2_b32 v113, v114, v112 offset0:8 offset1:74
	v_add_u32_e32 v115, v19, v77
	v_mul_f32_e32 v114, v181, v182
	v_mul_f32_e32 v112, v183, v184
	ds_write2_b32 v115, v114, v112 offset1:66
	v_mul_f32_e32 v114, v185, v186
	v_mul_f32_e32 v112, v187, v188
	ds_write2_b32 v115, v114, v112 offset0:132 offset1:198
	v_add_u32_e32 v115, 0x400, v115
	v_mul_f32_e32 v114, v189, v190
	v_mul_f32_e32 v112, v191, v192
	ds_write2_b32 v115, v114, v112 offset0:8 offset1:74
	v_mul_f32_e32 v114, v193, v194
	v_mul_f32_e32 v100, v195, v196
	ds_write2_b32 v115, v114, v100 offset0:140 offset1:206
	s_waitcnt lgkmcnt(0)
	ds_read2_b32 v[112:113], v81 offset1:33
	s_waitcnt lgkmcnt(0)
	v_cvt_pk_bf16_f32 v112, v112, v113
	ds_read2_b32 v[114:115], v81 offset0:66 offset1:99
	s_waitcnt lgkmcnt(0)
	v_cvt_pk_bf16_f32 v113, v114, v115
	ds_read2_b32 v[114:115], v81 offset0:132 offset1:165
	s_waitcnt lgkmcnt(0)
	v_cvt_pk_bf16_f32 v114, v114, v115
	ds_read2_b32 v[116:117], v81 offset0:198 offset1:231
	s_waitcnt lgkmcnt(0)
	v_cvt_pk_bf16_f32 v115, v116, v117
	v_or_b32_e32 v116, s0, v79
	v_lshl_add_u64 v[100:101], v[32:33], 0, s[10:11]
	v_lshlrev_b32_e32 v116, 11, v116
	v_mov_b32_e32 v117, v5
	v_lshl_add_u64 v[116:117], v[100:101], 0, v[116:117]
	v_add_co_u32_e32 v116, vcc, s25, v116
	s_nop 1
	v_addc_co_u32_e32 v117, vcc, 0, v117, vcc
	global_store_dwordx4 v[116:117], v[112:115], off
	ds_read2_b32 v[112:113], v81 offset0:8 offset1:41
	s_waitcnt lgkmcnt(0)
	v_cvt_pk_bf16_f32 v112, v112, v113
	ds_read2_b32 v[114:115], v81 offset0:74 offset1:107
	s_waitcnt lgkmcnt(0)
	v_cvt_pk_bf16_f32 v113, v114, v115
	ds_read2_b32 v[114:115], v81 offset0:140 offset1:173
	s_waitcnt lgkmcnt(0)
	v_cvt_pk_bf16_f32 v114, v114, v115
	ds_read2_b32 v[116:117], v81 offset0:206 offset1:239
	s_waitcnt lgkmcnt(0)
	v_cvt_pk_bf16_f32 v115, v116, v117
	v_or_b32_e32 v116, s0, v108
	v_lshlrev_b32_e32 v116, 11, v116
	v_mov_b32_e32 v117, v5
	v_lshl_add_u64 v[116:117], v[100:101], 0, v[116:117]
	v_add_co_u32_e32 v116, vcc, s25, v116
	s_nop 1
	v_addc_co_u32_e32 v117, vcc, 0, v117, vcc
	global_store_dwordx4 v[116:117], v[112:115], off
	ds_read2_b32 v[112:113], v81 offset0:16 offset1:49
	s_waitcnt lgkmcnt(0)
	v_cvt_pk_bf16_f32 v112, v112, v113
	ds_read2_b32 v[114:115], v81 offset0:82 offset1:115
	s_waitcnt lgkmcnt(0)
	v_cvt_pk_bf16_f32 v113, v114, v115
	ds_read2_b32 v[114:115], v81 offset0:148 offset1:181
	s_waitcnt lgkmcnt(0)
	v_cvt_pk_bf16_f32 v114, v114, v115
	ds_read2_b32 v[116:117], v81 offset0:214 offset1:247
	s_waitcnt lgkmcnt(0)
	v_cvt_pk_bf16_f32 v115, v116, v117
	v_or_b32_e32 v116, s0, v109
	v_lshlrev_b32_e32 v116, 11, v116
	v_mov_b32_e32 v117, v5
	v_lshl_add_u64 v[116:117], v[100:101], 0, v[116:117]
	v_add_co_u32_e32 v116, vcc, s25, v116
	s_nop 1
	v_addc_co_u32_e32 v117, vcc, 0, v117, vcc
	global_store_dwordx4 v[116:117], v[112:115], off
	ds_read2_b32 v[112:113], v81 offset0:24 offset1:57
	s_waitcnt lgkmcnt(0)
	v_cvt_pk_bf16_f32 v112, v112, v113
	ds_read2_b32 v[114:115], v81 offset0:90 offset1:123
	s_waitcnt lgkmcnt(0)
	v_cvt_pk_bf16_f32 v113, v114, v115
	ds_read2_b32 v[114:115], v81 offset0:156 offset1:189
	s_waitcnt lgkmcnt(0)
	v_cvt_pk_bf16_f32 v114, v114, v115
	ds_read2_b32 v[116:117], v81 offset0:222 offset1:255
	s_waitcnt lgkmcnt(0)
	v_cvt_pk_bf16_f32 v115, v116, v117
	v_or_b32_e32 v116, s0, v110
	v_lshlrev_b32_e32 v116, 11, v116
	v_mov_b32_e32 v117, v5
	v_lshl_add_u64 v[100:101], v[100:101], 0, v[116:117]
	v_add_co_u32_e32 v100, vcc, 0x20000, v100
	s_nop 1
	v_addc_co_u32_e32 v101, vcc, 0, v101, vcc
	global_store_dwordx4 v[100:101], v[112:115], off
	s_waitcnt lgkmcnt(0)

.LBB0_41:
	s_andn2_b64 vcc, exec, s[0:1]
	s_cbranch_vccnz .LBB0_43
	s_and_b32 s1, s21, 0x1fc0
	s_and_b32 s0, s21, 32
	s_lshl_b32 s10, s0, 2
	v_or_b32_e32 v114, s1, v3
	v_lshl_add_u64 v[100:101], v[30:31], 0, s[10:11]
	v_lshlrev_b32_e32 v112, 8, v114
	v_mov_b32_e32 v113, v5
	v_lshl_add_u64 v[112:113], v[100:101], 0, v[112:113]
	global_load_dword v125, v[112:113], off
	v_lshlrev_b32_e32 v113, 2, v114
	global_load_dword v128, v113, s[8:9]
	v_or_b32_e32 v116, s1, v39
	v_lshlrev_b32_e32 v112, 8, v116
	v_mov_b32_e32 v113, v5
	v_lshl_add_u64 v[112:113], v[100:101], 0, v[112:113]
	global_load_dword v130, v[112:113], off
	v_lshlrev_b32_e32 v113, 2, v116
	global_load_dword v131, v113, s[8:9]
	v_or_b32_e32 v116, s1, v43
	v_or_b32_e32 v114, s1, v41
	v_lshlrev_b32_e32 v112, 8, v114
	v_mov_b32_e32 v113, v5
	v_lshl_add_u64 v[112:113], v[100:101], 0, v[112:113]
	global_load_dword v132, v[112:113], off
	v_lshlrev_b32_e32 v113, 2, v114
	global_load_dword v133, v113, s[8:9]
	v_lshlrev_b32_e32 v112, 8, v116
	v_mov_b32_e32 v113, v5
	v_lshl_add_u64 v[112:113], v[100:101], 0, v[112:113]
	global_load_dword v134, v[112:113], off
	v_lshlrev_b32_e32 v113, 2, v116
	global_load_dword v135, v113, s[8:9]
	v_or_b32_e32 v116, s1, v47
	v_or_b32_e32 v114, s1, v45
	v_lshlrev_b32_e32 v112, 8, v114
	v_mov_b32_e32 v113, v5
	v_lshl_add_u64 v[112:113], v[100:101], 0, v[112:113]
	global_load_dword v136, v[112:113], off
	v_lshlrev_b32_e32 v113, 2, v114
	global_load_dword v137, v113, s[8:9]
	v_lshlrev_b32_e32 v112, 8, v116
	v_mov_b32_e32 v113, v5
	v_lshl_add_u64 v[112:113], v[100:101], 0, v[112:113]
	global_load_dword v138, v[112:113], off
	v_lshlrev_b32_e32 v113, 2, v116
	global_load_dword v139, v113, s[8:9]
	v_or_b32_e32 v116, s1, v53
	v_or_b32_e32 v114, s1, v49
	v_lshlrev_b32_e32 v112, 8, v114
	v_mov_b32_e32 v113, v5
	v_lshl_add_u64 v[112:113], v[100:101], 0, v[112:113]
	global_load_dword v140, v[112:113], off
	v_lshlrev_b32_e32 v113, 2, v114
	global_load_dword v141, v113, s[8:9]
	v_lshlrev_b32_e32 v112, 8, v116
	v_mov_b32_e32 v113, v5
	v_lshl_add_u64 v[112:113], v[100:101], 0, v[112:113]
	global_load_dword v142, v[112:113], off
	v_lshlrev_b32_e32 v113, 2, v116
	global_load_dword v143, v113, s[8:9]
	v_or_b32_e32 v116, s1, v57
	v_or_b32_e32 v114, s1, v55
	v_lshlrev_b32_e32 v112, 8, v114
	v_mov_b32_e32 v113, v5
	v_lshl_add_u64 v[112:113], v[100:101], 0, v[112:113]
	global_load_dword v144, v[112:113], off
	v_lshlrev_b32_e32 v113, 2, v114
	global_load_dword v145, v113, s[8:9]
	v_lshlrev_b32_e32 v112, 8, v116
	v_mov_b32_e32 v113, v5
	v_lshl_add_u64 v[112:113], v[100:101], 0, v[112:113]
	global_load_dword v146, v[112:113], off
	v_lshlrev_b32_e32 v113, 2, v116
	global_load_dword v148, v113, s[8:9]
	v_or_b32_e32 v116, s1, v61
	v_or_b32_e32 v114, s1, v59
	v_lshlrev_b32_e32 v112, 8, v114
	v_mov_b32_e32 v113, v5
	v_lshl_add_u64 v[112:113], v[100:101], 0, v[112:113]
	global_load_dword v150, v[112:113], off
	v_lshlrev_b32_e32 v113, 2, v114
	global_load_dword v151, v113, s[8:9]
	v_lshlrev_b32_e32 v112, 8, v116
	v_mov_b32_e32 v113, v5
	v_lshl_add_u64 v[112:113], v[100:101], 0, v[112:113]
	global_load_dword v152, v[112:113], off
	v_lshlrev_b32_e32 v113, 2, v116
	global_load_dword v153, v113, s[8:9]
	v_or_b32_e32 v116, s1, v67
	v_or_b32_e32 v114, s1, v63
	v_lshlrev_b32_e32 v112, 8, v114
	v_mov_b32_e32 v113, v5
	v_lshl_add_u64 v[112:113], v[100:101], 0, v[112:113]
	global_load_dword v154, v[112:113], off
	v_lshlrev_b32_e32 v113, 2, v114
	global_load_dword v155, v113, s[8:9]
	v_lshlrev_b32_e32 v112, 8, v116
	v_mov_b32_e32 v113, v5
	v_lshl_add_u64 v[112:113], v[100:101], 0, v[112:113]
	global_load_dword v156, v[112:113], off
	v_lshlrev_b32_e32 v113, 2, v116
	global_load_dword v157, v113, s[8:9]
	v_or_b32_e32 v116, s1, v71
	v_or_b32_e32 v114, s1, v69
	v_lshlrev_b32_e32 v112, 8, v114
	v_mov_b32_e32 v113, v5
	v_lshl_add_u64 v[112:113], v[100:101], 0, v[112:113]
	global_load_dword v158, v[112:113], off
	v_lshlrev_b32_e32 v113, 2, v114
	global_load_dword v159, v113, s[8:9]
	v_lshlrev_b32_e32 v112, 8, v116
	v_mov_b32_e32 v113, v5
	v_lshl_add_u64 v[112:113], v[100:101], 0, v[112:113]
	global_load_dword v160, v[112:113], off
	v_lshlrev_b32_e32 v113, 2, v116
	global_load_dword v161, v113, s[8:9]
	v_or_b32_e32 v116, s1, v83
	v_or_b32_e32 v114, s1, v73
	v_lshlrev_b32_e32 v112, 8, v114
	v_mov_b32_e32 v113, v5
	v_lshl_add_u64 v[112:113], v[100:101], 0, v[112:113]
	global_load_dword v162, v[112:113], off
	v_lshlrev_b32_e32 v113, 2, v114
	global_load_dword v163, v113, s[8:9]
	v_lshlrev_b32_e32 v112, 8, v116
	v_mov_b32_e32 v113, v5
	v_lshl_add_u64 v[112:113], v[100:101], 0, v[112:113]
	global_load_dword v164, v[112:113], off
	v_lshlrev_b32_e32 v113, 2, v116
	global_load_dword v165, v113, s[8:9]
	v_or_b32_e32 v116, s1, v87
	v_or_b32_e32 v114, s1, v85
	v_lshlrev_b32_e32 v112, 8, v114
	v_mov_b32_e32 v113, v5
	v_lshl_add_u64 v[112:113], v[100:101], 0, v[112:113]
	global_load_dword v166, v[112:113], off
	v_lshlrev_b32_e32 v113, 2, v114
	global_load_dword v168, v113, s[8:9]
	v_lshlrev_b32_e32 v112, 8, v116
	v_mov_b32_e32 v113, v5
	v_lshl_add_u64 v[112:113], v[100:101], 0, v[112:113]
	global_load_dword v170, v[112:113], off
	v_lshlrev_b32_e32 v113, 2, v116
	global_load_dword v171, v113, s[8:9]
	v_or_b32_e32 v116, s1, v91
	v_or_b32_e32 v114, s1, v89
	v_lshlrev_b32_e32 v112, 8, v114
	v_mov_b32_e32 v113, v5
	v_lshl_add_u64 v[112:113], v[100:101], 0, v[112:113]
	global_load_dword v172, v[112:113], off
	v_lshlrev_b32_e32 v113, 2, v114
	global_load_dword v173, v113, s[8:9]
	v_lshlrev_b32_e32 v112, 8, v116
	v_mov_b32_e32 v113, v5
	v_lshl_add_u64 v[112:113], v[100:101], 0, v[112:113]
	global_load_dword v174, v[112:113], off
	v_lshlrev_b32_e32 v113, 2, v116
	global_load_dword v176, v113, s[8:9]
	v_or_b32_e32 v116, s1, v95
	v_or_b32_e32 v114, s1, v93
	v_lshlrev_b32_e32 v112, 8, v114
	v_mov_b32_e32 v113, v5
	v_lshl_add_u64 v[112:113], v[100:101], 0, v[112:113]
	global_load_dword v177, v[112:113], off
	v_lshlrev_b32_e32 v113, 2, v114
	global_load_dword v178, v113, s[8:9]
	v_lshlrev_b32_e32 v112, 8, v116
	v_mov_b32_e32 v113, v5
	v_lshl_add_u64 v[112:113], v[100:101], 0, v[112:113]
	global_load_dword v179, v[112:113], off
	v_lshlrev_b32_e32 v113, 2, v116
	global_load_dword v180, v113, s[8:9]
	v_or_b32_e32 v116, s1, v99
	v_or_b32_e32 v114, s1, v97
	v_lshlrev_b32_e32 v112, 8, v114
	v_mov_b32_e32 v113, v5
	v_lshl_add_u64 v[112:113], v[100:101], 0, v[112:113]
	s_waitcnt vmcnt(16)
	global_load_dword v181, v[112:113], off
	v_lshlrev_b32_e32 v113, 2, v114
	global_load_dword v182, v113, s[8:9]
	v_lshlrev_b32_e32 v112, 8, v116
	v_mov_b32_e32 v113, v5
	v_lshl_add_u64 v[112:113], v[100:101], 0, v[112:113]
	global_load_dword v183, v[112:113], off
	v_lshlrev_b32_e32 v113, 2, v116
	global_load_dword v184, v113, s[8:9]
	v_or_b32_e32 v116, s1, v103
	v_or_b32_e32 v114, s1, v102
	v_lshlrev_b32_e32 v112, 8, v114
	v_mov_b32_e32 v113, v5
	v_lshl_add_u64 v[112:113], v[100:101], 0, v[112:113]
	global_load_dword v185, v[112:113], off
	v_lshlrev_b32_e32 v113, 2, v114
	global_load_dword v186, v113, s[8:9]
	v_lshlrev_b32_e32 v112, 8, v116
	v_mov_b32_e32 v113, v5
	v_lshl_add_u64 v[112:113], v[100:101], 0, v[112:113]
	global_load_dword v187, v[112:113], off
	v_lshlrev_b32_e32 v113, 2, v116
	global_load_dword v188, v113, s[8:9]
	v_or_b32_e32 v116, s1, v105
	v_or_b32_e32 v114, s1, v104
	v_lshlrev_b32_e32 v112, 8, v114
	v_mov_b32_e32 v113, v5
	v_lshl_add_u64 v[112:113], v[100:101], 0, v[112:113]
	global_load_dword v189, v[112:113], off
	v_lshlrev_b32_e32 v113, 2, v114
	global_load_dword v190, v113, s[8:9]
	v_lshlrev_b32_e32 v112, 8, v116
	v_mov_b32_e32 v113, v5
	v_lshl_add_u64 v[112:113], v[100:101], 0, v[112:113]
	global_load_dword v191, v[112:113], off
	v_lshlrev_b32_e32 v113, 2, v116
	global_load_dword v192, v113, s[8:9]
	v_or_b32_e32 v116, s1, v107
	v_or_b32_e32 v114, s1, v106
	v_lshlrev_b32_e32 v112, 8, v114
	v_mov_b32_e32 v113, v5
	v_lshl_add_u64 v[112:113], v[100:101], 0, v[112:113]
	global_load_dword v193, v[112:113], off
	v_lshlrev_b32_e32 v113, 2, v114
	global_load_dword v194, v113, s[8:9]
	v_lshlrev_b32_e32 v112, 8, v116
	v_mov_b32_e32 v113, v5
	v_lshl_add_u64 v[100:101], v[100:101], 0, v[112:113]
	global_load_dword v195, v[100:101], off
	v_lshlrev_b32_e32 v101, 2, v116
	global_load_dword v196, v101, s[8:9]
	s_waitcnt vmcnt(0)
	v_add_u32_e32 v115, v19, v37
	s_lshl_b32 s10, s1, 1
	v_sub_f32_e32 v113, 1.0, v128
	v_mul_f32_e32 v114, v125, v113
	v_sub_f32_e32 v113, 1.0, v131
	v_mul_f32_e32 v112, v130, v113
	ds_write2_b32 v115, v114, v112 offset1:66
	v_sub_f32_e32 v113, 1.0, v133
	v_mul_f32_e32 v114, v132, v113
	v_sub_f32_e32 v113, 1.0, v135
	v_mul_f32_e32 v112, v134, v113
	ds_write2_b32 v115, v114, v112 offset0:132 offset1:198
	v_sub_f32_e32 v113, 1.0, v137
	v_mul_f32_e32 v114, v136, v113
	v_sub_f32_e32 v113, 1.0, v139
	v_mul_f32_e32 v112, v138, v113
	v_add_u32_e32 v113, 0x400, v115
	ds_write2_b32 v113, v114, v112 offset0:8 offset1:74
	v_add_u32_e32 v115, v19, v51
	v_sub_f32_e32 v113, 1.0, v141
	v_mul_f32_e32 v114, v140, v113
	v_sub_f32_e32 v113, 1.0, v143
	v_mul_f32_e32 v112, v142, v113
	ds_write2_b32 v115, v114, v112 offset1:66
	v_sub_f32_e32 v113, 1.0, v145
	v_mul_f32_e32 v114, v144, v113
	v_sub_f32_e32 v113, 1.0, v148
	v_mul_f32_e32 v112, v146, v113
	ds_write2_b32 v115, v114, v112 offset0:132 offset1:198
	v_sub_f32_e32 v113, 1.0, v151
	v_mul_f32_e32 v114, v150, v113
	v_sub_f32_e32 v113, 1.0, v153
	v_mul_f32_e32 v112, v152, v113
	v_add_u32_e32 v113, 0x400, v115
	ds_write2_b32 v113, v114, v112 offset0:8 offset1:74
	v_add_u32_e32 v115, v19, v65
	v_sub_f32_e32 v113, 1.0, v155
	v_mul_f32_e32 v114, v154, v113
	v_sub_f32_e32 v113, 1.0, v157
	v_mul_f32_e32 v112, v156, v113
	ds_write2_b32 v115, v114, v112 offset1:66
	v_sub_f32_e32 v113, 1.0, v159
	v_mul_f32_e32 v114, v158, v113
	v_sub_f32_e32 v113, 1.0, v161
	v_mul_f32_e32 v112, v160, v113
	ds_write2_b32 v115, v114, v112 offset0:132 offset1:198
	v_sub_f32_e32 v113, 1.0, v163
	v_mul_f32_e32 v114, v162, v113
	v_sub_f32_e32 v113, 1.0, v165
	v_mul_f32_e32 v112, v164, v113
	v_add_u32_e32 v113, 0x400, v115
	ds_write2_b32 v113, v114, v112 offset0:8 offset1:74
	v_add_u32_e32 v115, v19, v75
	v_sub_f32_e32 v113, 1.0, v168
	v_mul_f32_e32 v114, v166, v113
	v_sub_f32_e32 v113, 1.0, v171
	v_mul_f32_e32 v112, v170, v113
	ds_write2_b32 v115, v114, v112 offset1:66
	v_sub_f32_e32 v113, 1.0, v173
	v_mul_f32_e32 v114, v172, v113
	v_sub_f32_e32 v113, 1.0, v176
	v_mul_f32_e32 v112, v174, v113
	ds_write2_b32 v115, v114, v112 offset0:132 offset1:198
	v_sub_f32_e32 v113, 1.0, v178
	v_mul_f32_e32 v114, v177, v113
	v_sub_f32_e32 v113, 1.0, v180
	v_mul_f32_e32 v112, v179, v113
	v_add_u32_e32 v113, 0x400, v115
	ds_write2_b32 v113, v114, v112 offset0:8 offset1:74
	v_add_u32_e32 v115, v19, v77
	v_sub_f32_e32 v113, 1.0, v182
	v_mul_f32_e32 v114, v181, v113
	v_sub_f32_e32 v113, 1.0, v184
	v_mul_f32_e32 v112, v183, v113
	ds_write2_b32 v115, v114, v112 offset1:66
	v_sub_f32_e32 v113, 1.0, v186
	v_mul_f32_e32 v114, v185, v113
	v_sub_f32_e32 v113, 1.0, v188
	v_mul_f32_e32 v112, v187, v113
	ds_write2_b32 v115, v114, v112 offset0:132 offset1:198
	v_add_u32_e32 v115, 0x400, v115
	v_sub_f32_e32 v113, 1.0, v190
	v_mul_f32_e32 v114, v189, v113
	v_sub_f32_e32 v113, 1.0, v192
	v_mul_f32_e32 v112, v191, v113
	ds_write2_b32 v115, v114, v112 offset0:8 offset1:74
	v_sub_f32_e32 v113, 1.0, v194
	v_mul_f32_e32 v114, v193, v113
	v_sub_f32_e32 v101, 1.0, v196
	v_mul_f32_e32 v100, v195, v101
	ds_write2_b32 v115, v114, v100 offset0:140 offset1:206
	s_waitcnt lgkmcnt(0)
	ds_read2_b32 v[112:113], v81 offset1:33
	s_waitcnt lgkmcnt(0)
	v_cvt_pk_bf16_f32 v112, v112, v113
	ds_read2_b32 v[114:115], v81 offset0:66 offset1:99
	s_waitcnt lgkmcnt(0)
	v_cvt_pk_bf16_f32 v113, v114, v115
	ds_read2_b32 v[114:115], v81 offset0:132 offset1:165
	s_waitcnt lgkmcnt(0)
	v_cvt_pk_bf16_f32 v114, v114, v115
	ds_read2_b32 v[116:117], v81 offset0:198 offset1:231
	s_waitcnt lgkmcnt(0)
	v_cvt_pk_bf16_f32 v115, v116, v117
	v_or_b32_e32 v116, s0, v79
	v_lshl_add_u64 v[100:101], v[32:33], 0, s[10:11]
	v_lshlrev_b32_e32 v116, 11, v116
	v_mov_b32_e32 v117, v5
	v_lshl_add_u64 v[116:117], v[100:101], 0, v[116:117]
	global_store_dwordx4 v[116:117], v[112:115], off
	ds_read2_b32 v[112:113], v81 offset0:8 offset1:41
	s_waitcnt lgkmcnt(0)
	v_cvt_pk_bf16_f32 v112, v112, v113
	ds_read2_b32 v[114:115], v81 offset0:74 offset1:107
	s_waitcnt lgkmcnt(0)
	v_cvt_pk_bf16_f32 v113, v114, v115
	ds_read2_b32 v[114:115], v81 offset0:140 offset1:173
	s_waitcnt lgkmcnt(0)
	v_cvt_pk_bf16_f32 v114, v114, v115
	ds_read2_b32 v[116:117], v81 offset0:206 offset1:239
	s_waitcnt lgkmcnt(0)
	v_cvt_pk_bf16_f32 v115, v116, v117
	v_or_b32_e32 v116, s0, v108
	v_lshlrev_b32_e32 v116, 11, v116
	v_mov_b32_e32 v117, v5
	v_lshl_add_u64 v[116:117], v[100:101], 0, v[116:117]
	global_store_dwordx4 v[116:117], v[112:115], off
	ds_read2_b32 v[112:113], v81 offset0:16 offset1:49
	s_waitcnt lgkmcnt(0)
	v_cvt_pk_bf16_f32 v112, v112, v113
	ds_read2_b32 v[114:115], v81 offset0:82 offset1:115
	s_waitcnt lgkmcnt(0)
	v_cvt_pk_bf16_f32 v113, v114, v115
	ds_read2_b32 v[114:115], v81 offset0:148 offset1:181
	s_waitcnt lgkmcnt(0)
	v_cvt_pk_bf16_f32 v114, v114, v115
	ds_read2_b32 v[116:117], v81 offset0:214 offset1:247
	s_waitcnt lgkmcnt(0)
	v_cvt_pk_bf16_f32 v115, v116, v117
	v_or_b32_e32 v116, s0, v109
	v_lshlrev_b32_e32 v116, 11, v116
	v_mov_b32_e32 v117, v5
	v_lshl_add_u64 v[116:117], v[100:101], 0, v[116:117]
	global_store_dwordx4 v[116:117], v[112:115], off
	ds_read2_b32 v[112:113], v81 offset0:24 offset1:57
	s_waitcnt lgkmcnt(0)
	v_cvt_pk_bf16_f32 v112, v112, v113
	ds_read2_b32 v[114:115], v81 offset0:90 offset1:123
	s_waitcnt lgkmcnt(0)
	v_cvt_pk_bf16_f32 v113, v114, v115
	ds_read2_b32 v[114:115], v81 offset0:156 offset1:189
	s_waitcnt lgkmcnt(0)
	v_cvt_pk_bf16_f32 v114, v114, v115
	ds_read2_b32 v[116:117], v81 offset0:222 offset1:255
	s_waitcnt lgkmcnt(0)
	v_cvt_pk_bf16_f32 v115, v116, v117
	v_or_b32_e32 v116, s0, v110
	v_lshlrev_b32_e32 v116, 11, v116
	v_mov_b32_e32 v117, v5
	v_lshl_add_u64 v[100:101], v[100:101], 0, v[116:117]
	global_store_dwordx4 v[100:101], v[112:115], off
	s_waitcnt lgkmcnt(0)

.LBB0_44:
	s_andn2_b64 vcc, exec, s[0:1]
	s_cbranch_vccnz .LBB0_9
	s_ashr_i32 s0, s3, 31
	s_lshr_b32 s0, s0, 23
	s_add_i32 s10, s3, s0
	s_ashr_i32 s0, s10, 9
	s_ashr_i32 s1, s0, 31
	s_lshl_b64 s[14:15], s[0:1], 22
	s_add_u32 s17, s46, s14
	s_addc_u32 s28, s47, s15
	s_and_b32 s1, s10, 0xfe00
	s_sub_i32 s1, s3, s1
	s_sext_i32_i16 s10, s1
	s_bfe_u32 s10, s10, 0x5001a
	s_add_i32 s10, s1, s10
	s_sext_i32_i16 s14, s10
	s_and_b32 s10, s10, 0xffe0
	s_sub_i32 s1, s1, s10
	s_sext_i32_i16 s10, s1
	s_lshl_b32 s14, s14, 1
	s_and_b32 s16, s14, 0xffffffc0
	s_lshl_b32 s14, s10, 5
	s_ashr_i32 s15, s14, 31
	s_lshl_b64 s[26:27], s[14:15], 2
	s_add_u32 s26, s17, s26
	v_or_b32_e32 v112, s16, v3
	s_addc_u32 s27, s28, s27
	v_ashrrev_i32_e32 v113, 31, v112
	v_lshl_add_u64 v[100:101], s[26:27], 0, v[4:5]
	v_lshlrev_b64 v[112:113], 12, v[112:113]
	v_lshl_add_u64 v[112:113], v[100:101], 0, v[112:113]
	global_load_dword v125, v[112:113], off
	v_or_b32_e32 v112, s16, v39
	v_ashrrev_i32_e32 v113, 31, v112
	v_lshlrev_b64 v[112:113], 12, v[112:113]
	v_lshl_add_u64 v[112:113], v[100:101], 0, v[112:113]
	global_load_dword v128, v[112:113], off
	v_or_b32_e32 v112, s16, v41
	v_ashrrev_i32_e32 v113, 31, v112
	v_lshlrev_b64 v[112:113], 12, v[112:113]
	v_lshl_add_u64 v[112:113], v[100:101], 0, v[112:113]
	global_load_dword v130, v[112:113], off
	v_or_b32_e32 v112, s16, v43
	v_ashrrev_i32_e32 v113, 31, v112
	v_lshlrev_b64 v[112:113], 12, v[112:113]
	v_lshl_add_u64 v[112:113], v[100:101], 0, v[112:113]
	global_load_dword v131, v[112:113], off
	v_or_b32_e32 v112, s16, v45
	v_ashrrev_i32_e32 v113, 31, v112
	v_lshlrev_b64 v[112:113], 12, v[112:113]
	v_lshl_add_u64 v[112:113], v[100:101], 0, v[112:113]
	global_load_dword v132, v[112:113], off
	v_or_b32_e32 v112, s16, v47
	v_ashrrev_i32_e32 v113, 31, v112
	v_lshlrev_b64 v[112:113], 12, v[112:113]
	v_lshl_add_u64 v[112:113], v[100:101], 0, v[112:113]
	global_load_dword v133, v[112:113], off
	v_or_b32_e32 v112, s16, v49
	v_ashrrev_i32_e32 v113, 31, v112
	v_lshlrev_b64 v[112:113], 12, v[112:113]
	v_lshl_add_u64 v[112:113], v[100:101], 0, v[112:113]
	global_load_dword v134, v[112:113], off
	v_or_b32_e32 v112, s16, v53
	v_ashrrev_i32_e32 v113, 31, v112
	v_lshlrev_b64 v[112:113], 12, v[112:113]
	v_lshl_add_u64 v[112:113], v[100:101], 0, v[112:113]
	global_load_dword v135, v[112:113], off
	v_or_b32_e32 v112, s16, v55
	v_ashrrev_i32_e32 v113, 31, v112
	v_lshlrev_b64 v[112:113], 12, v[112:113]
	v_lshl_add_u64 v[112:113], v[100:101], 0, v[112:113]
	global_load_dword v136, v[112:113], off
	v_or_b32_e32 v112, s16, v57
	v_ashrrev_i32_e32 v113, 31, v112
	v_lshlrev_b64 v[112:113], 12, v[112:113]
	v_lshl_add_u64 v[112:113], v[100:101], 0, v[112:113]
	global_load_dword v137, v[112:113], off
	v_or_b32_e32 v112, s16, v59
	v_ashrrev_i32_e32 v113, 31, v112
	v_lshlrev_b64 v[112:113], 12, v[112:113]
	v_lshl_add_u64 v[112:113], v[100:101], 0, v[112:113]
	global_load_dword v138, v[112:113], off
	v_or_b32_e32 v112, s16, v61
	v_ashrrev_i32_e32 v113, 31, v112
	v_lshlrev_b64 v[112:113], 12, v[112:113]
	v_lshl_add_u64 v[112:113], v[100:101], 0, v[112:113]
	global_load_dword v139, v[112:113], off
	v_or_b32_e32 v112, s16, v63
	v_ashrrev_i32_e32 v113, 31, v112
	v_lshlrev_b64 v[112:113], 12, v[112:113]
	v_lshl_add_u64 v[112:113], v[100:101], 0, v[112:113]
	global_load_dword v140, v[112:113], off
	v_or_b32_e32 v112, s16, v67
	v_ashrrev_i32_e32 v113, 31, v112
	v_lshlrev_b64 v[112:113], 12, v[112:113]
	v_lshl_add_u64 v[112:113], v[100:101], 0, v[112:113]
	global_load_dword v141, v[112:113], off
	v_or_b32_e32 v112, s16, v69
	v_ashrrev_i32_e32 v113, 31, v112
	v_lshlrev_b64 v[112:113], 12, v[112:113]
	v_lshl_add_u64 v[112:113], v[100:101], 0, v[112:113]
	global_load_dword v142, v[112:113], off
	v_or_b32_e32 v112, s16, v71
	v_ashrrev_i32_e32 v113, 31, v112
	v_lshlrev_b64 v[112:113], 12, v[112:113]
	v_lshl_add_u64 v[112:113], v[100:101], 0, v[112:113]
	global_load_dword v143, v[112:113], off
	v_or_b32_e32 v112, s16, v73
	v_ashrrev_i32_e32 v113, 31, v112
	v_lshlrev_b64 v[112:113], 12, v[112:113]
	v_lshl_add_u64 v[112:113], v[100:101], 0, v[112:113]
	global_load_dword v144, v[112:113], off
	v_or_b32_e32 v112, s16, v83
	v_ashrrev_i32_e32 v113, 31, v112
	v_lshlrev_b64 v[112:113], 12, v[112:113]
	v_lshl_add_u64 v[112:113], v[100:101], 0, v[112:113]
	global_load_dword v145, v[112:113], off
	v_or_b32_e32 v112, s16, v85
	v_ashrrev_i32_e32 v113, 31, v112
	v_lshlrev_b64 v[112:113], 12, v[112:113]
	v_lshl_add_u64 v[112:113], v[100:101], 0, v[112:113]
	global_load_dword v146, v[112:113], off
	v_or_b32_e32 v112, s16, v87
	v_ashrrev_i32_e32 v113, 31, v112
	v_lshlrev_b64 v[112:113], 12, v[112:113]
	v_lshl_add_u64 v[112:113], v[100:101], 0, v[112:113]
	global_load_dword v148, v[112:113], off
	v_or_b32_e32 v112, s16, v89
	v_ashrrev_i32_e32 v113, 31, v112
	v_lshlrev_b64 v[112:113], 12, v[112:113]
	v_lshl_add_u64 v[112:113], v[100:101], 0, v[112:113]
	global_load_dword v150, v[112:113], off
	v_or_b32_e32 v112, s16, v91
	v_ashrrev_i32_e32 v113, 31, v112
	v_lshlrev_b64 v[112:113], 12, v[112:113]
	v_lshl_add_u64 v[112:113], v[100:101], 0, v[112:113]
	global_load_dword v151, v[112:113], off
	v_or_b32_e32 v112, s16, v93
	v_ashrrev_i32_e32 v113, 31, v112
	v_lshlrev_b64 v[112:113], 12, v[112:113]
	v_lshl_add_u64 v[112:113], v[100:101], 0, v[112:113]
	global_load_dword v152, v[112:113], off
	v_or_b32_e32 v112, s16, v95
	v_ashrrev_i32_e32 v113, 31, v112
	v_lshlrev_b64 v[112:113], 12, v[112:113]
	v_lshl_add_u64 v[112:113], v[100:101], 0, v[112:113]
	global_load_dword v153, v[112:113], off
	v_or_b32_e32 v112, s16, v97
	v_ashrrev_i32_e32 v113, 31, v112
	v_lshlrev_b64 v[112:113], 12, v[112:113]
	v_lshl_add_u64 v[112:113], v[100:101], 0, v[112:113]
	global_load_dword v154, v[112:113], off
	v_or_b32_e32 v112, s16, v99
	v_ashrrev_i32_e32 v113, 31, v112
	v_lshlrev_b64 v[112:113], 12, v[112:113]
	v_lshl_add_u64 v[112:113], v[100:101], 0, v[112:113]
	global_load_dword v155, v[112:113], off
	v_or_b32_e32 v112, s16, v102
	v_ashrrev_i32_e32 v113, 31, v112
	v_lshlrev_b64 v[112:113], 12, v[112:113]
	v_lshl_add_u64 v[112:113], v[100:101], 0, v[112:113]
	global_load_dword v156, v[112:113], off
	v_or_b32_e32 v112, s16, v103
	v_ashrrev_i32_e32 v113, 31, v112
	v_lshlrev_b64 v[112:113], 12, v[112:113]
	v_lshl_add_u64 v[112:113], v[100:101], 0, v[112:113]
	global_load_dword v157, v[112:113], off
	v_or_b32_e32 v112, s16, v104
	v_ashrrev_i32_e32 v113, 31, v112
	v_lshlrev_b64 v[112:113], 12, v[112:113]
	v_lshl_add_u64 v[112:113], v[100:101], 0, v[112:113]
	global_load_dword v158, v[112:113], off
	v_or_b32_e32 v112, s16, v105
	v_ashrrev_i32_e32 v113, 31, v112
	v_lshlrev_b64 v[112:113], 12, v[112:113]
	v_lshl_add_u64 v[112:113], v[100:101], 0, v[112:113]
	global_load_dword v159, v[112:113], off
	v_or_b32_e32 v112, s16, v106
	v_ashrrev_i32_e32 v113, 31, v112
	v_lshlrev_b64 v[112:113], 12, v[112:113]
	v_lshl_add_u64 v[112:113], v[100:101], 0, v[112:113]
	global_load_dword v160, v[112:113], off
	v_or_b32_e32 v112, s16, v107
	v_ashrrev_i32_e32 v113, 31, v112
	v_lshlrev_b64 v[112:113], 12, v[112:113]
	v_lshl_add_u64 v[100:101], v[100:101], 0, v[112:113]
	global_load_dword v161, v[100:101], off
	s_waitcnt vmcnt(0)
	s_lshl_b32 s0, s0, 10
	v_add_u32_e32 v115, v19, v37
	s_and_b32 s10, s14, 0xffffffc0
	s_ashr_i32 s17, s16, 31
	s_and_b32 s1, s1, 0x8001
	s_cmpk_eq_u32 s1, 0x8000
	v_or_b32_e32 v118, s10, v111
	s_cselect_b64 vcc, -1, 0
	ds_write2_b32 v115, v125, v128 offset1:66
	ds_write2_b32 v115, v130, v131 offset0:132 offset1:198
	v_add_u32_e32 v113, 0x400, v115
	v_add_u32_e32 v115, v19, v51
	ds_write2_b32 v113, v132, v133 offset0:8 offset1:74
	ds_write2_b32 v115, v134, v135 offset1:66
	ds_write2_b32 v115, v136, v137 offset0:132 offset1:198
	v_add_u32_e32 v113, 0x400, v115
	v_add_u32_e32 v115, v19, v65
	ds_write2_b32 v113, v138, v139 offset0:8 offset1:74
	ds_write2_b32 v115, v140, v141 offset1:66
	ds_write2_b32 v115, v142, v143 offset0:132 offset1:198
	v_add_u32_e32 v113, 0x400, v115
	v_add_u32_e32 v115, v19, v75
	ds_write2_b32 v113, v144, v145 offset0:8 offset1:74
	ds_write2_b32 v115, v146, v148 offset1:66
	ds_write2_b32 v115, v150, v151 offset0:132 offset1:198
	v_add_u32_e32 v113, 0x400, v115
	v_add_u32_e32 v115, v19, v77
	ds_write2_b32 v113, v152, v153 offset0:8 offset1:74
	ds_write2_b32 v115, v154, v155 offset1:66
	ds_write2_b32 v115, v156, v157 offset0:132 offset1:198
	v_add_u32_e32 v115, 0x400, v115
	ds_write2_b32 v115, v158, v159 offset0:8 offset1:74
	ds_write2_b32 v115, v160, v161 offset0:140 offset1:206
	s_waitcnt lgkmcnt(0)
	ds_read2_b32 v[112:113], v81 offset1:33
	s_waitcnt lgkmcnt(0)
	v_cvt_pk_bf16_f32 v112, v112, v113
	ds_read2_b32 v[114:115], v81 offset0:66 offset1:99
	s_waitcnt lgkmcnt(0)
	v_cvt_pk_bf16_f32 v113, v114, v115
	ds_read2_b32 v[114:115], v81 offset0:132 offset1:165
	s_waitcnt lgkmcnt(0)
	v_cvt_pk_bf16_f32 v114, v114, v115
	ds_read2_b32 v[116:117], v81 offset0:198 offset1:231
	s_waitcnt lgkmcnt(0)
	v_cvt_pk_bf16_f32 v115, v116, v117
	v_or_b32_e32 v116, s14, v79
	v_cndmask_b32_e32 v116, v116, v118, vcc
	v_add_u32_e32 v116, s0, v116
	v_ashrrev_i32_e32 v117, 31, v116
	v_lshl_add_u64 v[100:101], s[16:17], 1, v[34:35]
	v_lshlrev_b64 v[116:117], 11, v[116:117]
	v_lshl_add_u64 v[116:117], v[100:101], 0, v[116:117]
	global_store_dwordx4 v[116:117], v[112:115], off
	ds_read2_b32 v[112:113], v81 offset0:8 offset1:41
	s_waitcnt lgkmcnt(0)
	v_cvt_pk_bf16_f32 v112, v112, v113
	ds_read2_b32 v[114:115], v81 offset0:74 offset1:107
	s_waitcnt lgkmcnt(0)
	v_cvt_pk_bf16_f32 v113, v114, v115
	ds_read2_b32 v[114:115], v81 offset0:140 offset1:173
	s_waitcnt lgkmcnt(0)
	v_cvt_pk_bf16_f32 v114, v114, v115
	ds_read2_b32 v[116:117], v81 offset0:206 offset1:239
	s_waitcnt lgkmcnt(0)
	v_cvt_pk_bf16_f32 v115, v116, v117
	v_or_b32_e32 v116, s14, v108
	v_or_b32_e32 v117, 1, v118
	v_cndmask_b32_e32 v116, v116, v117, vcc
	v_add_u32_e32 v116, s0, v116
	v_ashrrev_i32_e32 v117, 31, v116
	v_lshlrev_b64 v[116:117], 11, v[116:117]
	v_lshl_add_u64 v[116:117], v[100:101], 0, v[116:117]
	global_store_dwordx4 v[116:117], v[112:115], off
	ds_read2_b32 v[112:113], v81 offset0:16 offset1:49
	s_waitcnt lgkmcnt(0)
	v_cvt_pk_bf16_f32 v112, v112, v113
	ds_read2_b32 v[114:115], v81 offset0:82 offset1:115
	s_waitcnt lgkmcnt(0)
	v_cvt_pk_bf16_f32 v113, v114, v115
	ds_read2_b32 v[114:115], v81 offset0:148 offset1:181
	s_waitcnt lgkmcnt(0)
	v_cvt_pk_bf16_f32 v114, v114, v115
	ds_read2_b32 v[116:117], v81 offset0:214 offset1:247
	s_waitcnt lgkmcnt(0)
	v_cvt_pk_bf16_f32 v115, v116, v117
	v_or_b32_e32 v116, s0, v109
	v_add_u32_e32 v116, s14, v116
	v_ashrrev_i32_e32 v117, 31, v116
	v_lshlrev_b64 v[116:117], 11, v[116:117]
	v_lshl_add_u64 v[116:117], v[100:101], 0, v[116:117]
	global_store_dwordx4 v[116:117], v[112:115], off
	ds_read2_b32 v[112:113], v81 offset0:24 offset1:57
	s_waitcnt lgkmcnt(0)
	v_cvt_pk_bf16_f32 v112, v112, v113
	ds_read2_b32 v[114:115], v81 offset0:90 offset1:123
	s_waitcnt lgkmcnt(0)
	v_cvt_pk_bf16_f32 v113, v114, v115
	ds_read2_b32 v[114:115], v81 offset0:156 offset1:189
	s_waitcnt lgkmcnt(0)
	v_cvt_pk_bf16_f32 v114, v114, v115
	ds_read2_b32 v[116:117], v81 offset0:222 offset1:255
	s_waitcnt lgkmcnt(0)
	v_cvt_pk_bf16_f32 v115, v116, v117
	v_or_b32_e32 v116, s0, v110
	v_add_u32_e32 v116, s14, v116
	v_ashrrev_i32_e32 v117, 31, v116
	v_lshlrev_b64 v[116:117], 11, v[116:117]
	v_lshl_add_u64 v[100:101], v[100:101], 0, v[116:117]
	global_store_dwordx4 v[100:101], v[112:115], off
	s_waitcnt lgkmcnt(0)
	s_branch .LBB0_9
